# up-GEMM tokens interleaved over the four 16-row MFMA blocks (LDS row 16m+fr holds token 4fr+m) so conv neighbours sit in the same lane: packed FMAs replace most DPP taps; conversion read-back batched
# speedup vs baseline: 1.1098x; 1.0120x over previous
.LBB0_34:
	s_add_i32 s3, s70, -1
	s_mul_hi_i32 s4, s3, 0x92492493
	s_add_i32 s4, s4, s3
	s_lshr_b32 s5, s4, 31
	s_ashr_i32 s4, s4, 2
	s_add_i32 s79, s4, s5
	s_mul_i32 s4, s79, 7
	s_sub_i32 s80, s3, s4
	s_ashr_i32 s4, s79, 1
	v_writelane_b32 v239, s4, 47
	s_bitcmp1_b32 s79, 0
	s_mul_hi_i32 s3, s79, 0x12000
	v_writelane_b32 v239, s5, 48
	s_cselect_b64 s[4:5], -1, 0
	v_writelane_b32 v239, s4, 49
	s_mov_b64 s[66:67], 0
	s_mov_b64 s[84:85], 0
	v_writelane_b32 v239, s5, 50
	s_mul_i32 s4, s79, 0x12000
	v_readlane_b32 s6, v239, 29
	v_readlane_b32 s7, v239, 30
	s_add_u32 s4, s6, s4
	s_addc_u32 s5, s7, s3
	v_writelane_b32 v239, s4, 51
	s_mov_b64 s[6:7], s[70:71]
	s_cmp_lt_i32 s80, 3
	v_writelane_b32 v239, s5, 52
	s_mov_b64 s[4:5], -1
	v_writelane_b32 v239, s4, 53
	s_nop 1
	v_writelane_b32 v239, s5, 54
	v_writelane_b32 v239, s6, 55
	v_writelane_b32 v239, s7, 56
	s_cbranch_scc1 .LBB0_160
	s_cmp_gt_i32 s80, 3
	s_cbranch_scc0 .LBB0_63
	s_cmp_gt_i32 s80, 4
	s_cbranch_scc0 .LBB0_64
	s_cmp_eq_u32 s80, 5
	s_mov_b64 s[84:85], -1
	s_cbranch_scc0 .LBB0_81
	v_readlane_b32 s4, v239, 29
	v_readlane_b32 s5, v239, 30
	s_add_u32 s15, s4, 0x2700000
	s_addc_u32 s33, s5, 0
	s_cmpk_gt_i32 s78, 0x2bf
	v_readfirstlane_b32 s14, v210
	s_cbranch_scc1 .LBB0_66
	v_lshlrev_b32_e32 v0, 4, v210
	v_add_u32_e32 v1, 0x2000, v0
	v_ashrrev_i32_e32 v2, 31, v1
	v_lshrrev_b32_e32 v2, 22, v2
	v_add_u32_e32 v2, v1, v2
	v_ashrrev_i32_e32 v8, 10, v2
	v_mul_i32_i24_e32 v2, 0x400, v8
	v_sub_u32_e32 v1, v1, v2
	v_lshrrev_b32_e32 v2, 4, v1
	v_bitop3_b32 v1, v2, v1, 32 bitop3:0x6c
	v_writelane_b32 v239, s80, 59
	v_ashrrev_i32_e32 v2, 31, v1
	v_readlane_b32 s4, v239, 29
	v_lshrrev_b32_e32 v2, 26, v2
	v_readlane_b32 s5, v239, 30
	s_add_u32 s10, s4, 0x8900000
	v_add_u32_e32 v2, v1, v2
	v_lshlrev_b32_e32 v3, 3, v8
	s_addc_u32 s11, s5, 0
	s_mul_i32 s4, s79, 0xb00000
	v_ashrrev_i32_e32 v9, 6, v2
	v_and_b32_e32 v3, -16, v3
	s_mul_hi_i32 s3, s79, 0xb00000
	s_add_u32 s34, s15, s4
	v_add_u32_e32 v3, v9, v3
	s_addc_u32 s35, s33, s3
	v_and_b32_e32 v4, 3, v9
	s_mov_b32 s3, 0x1fffe0
	v_lshrrev_b32_e32 v5, 2, v3
	v_lshlrev_b32_e32 v6, 1, v3
	v_and_b32_e32 v2, 0xc0, v2
	v_and_or_b32 v4, v3, s3, v4
	v_and_b32_e32 v5, 4, v5
	v_and_b32_e32 v6, 24, v6
	v_sub_u32_e32 v1, v1, v2
	v_or3_b32 v4, v4, v5, v6
	v_lshlrev_b32_e32 v5, 5, v8
	v_ashrrev_i16_sdwa v1, v198, sext(v1) dst_sel:DWORD dst_unused:UNUSED_PAD src0_sel:DWORD src1_sel:BYTE_0
	v_and_b32_e32 v5, 32, v5
	v_bfe_i32 v10, v1, 0, 16
	v_add_lshl_u32 v1, v5, v10, 1
	v_lshl_add_u32 v160, v4, 11, v1
	v_lshl_add_u32 v162, v3, 11, v1
	v_bfe_i32 v1, v210, 27, 1
	v_lshrrev_b32_e32 v1, 22, v1
	v_add_u32_e32 v1, v0, v1
	v_and_b32_e32 v1, 0xfffffc00, v1
	v_sub_u32_e32 v0, v0, v1
	v_lshrrev_b32_e32 v1, 4, v0
	v_ashrrev_i32_e32 v2, 31, v210
	v_bitop3_b32 v0, v1, v0, 32 bitop3:0x6c
	v_lshrrev_b32_e32 v2, 26, v2
	v_ashrrev_i32_e32 v1, 31, v0
	v_add_u32_e32 v2, v210, v2
	v_lshrrev_b32_e32 v1, 26, v1
	v_ashrrev_i32_e32 v12, 6, v2
	v_add_u32_e32 v1, v0, v1
	v_lshlrev_b32_e32 v2, 3, v12
	v_ashrrev_i32_e32 v11, 6, v1
	v_and_b32_e32 v2, -16, v2
	v_add_u32_e32 v2, v11, v2
	v_and_b32_e32 v3, 3, v11
	v_and_or_b32 v3, v2, s3, v3
	s_ashr_i32 s3, s78, 31
	s_lshr_b32 s3, s3, 29
	v_writelane_b32 v238, s15, 6
	s_add_i32 s3, s78, s3
	v_writelane_b32 v238, s33, 7
	s_ashr_i32 s33, s14, 6
	s_and_b32 s4, s3, -8
	s_ashr_i32 s15, s14, 8
	s_lshl_b32 s13, s33, 10
	s_sub_i32 s4, s78, s4
	s_cmp_lt_i32 s4, 0
	s_movk_i32 s5, 0x59
	s_cselect_b32 s5, s5, 0x58
	s_mul_i32 s4, s4, s5
	s_ashr_i32 s3, s3, 3
	s_add_i32 s4, s4, s3
	s_mul_hi_i32 s3, s4, 0xd1745d17
	s_lshr_b32 s5, s3, 31
	s_ashr_i32 s3, s3, 7
	s_add_i32 s8, s3, s5
	s_mul_hi_i32 s3, s4, 0x2e8ba2e9
	s_lshr_b32 s5, s3, 31
	s_ashr_i32 s3, s3, 7
	s_add_i32 s3, s3, s5
	s_mulk_i32 s3, 0x2c0
	s_sub_i32 s3, s4, s3
	s_sext_i32_i16 s4, s3
	s_mulk_i32 s4, 0xba3
	s_lshr_b32 s5, s4, 31
	s_ashr_i32 s4, s4, 19
	s_add_i32 s4, s4, s5
	s_lshl_b32 s5, s4, 3
	s_mulk_i32 s4, 0xb0
	s_sub_i32 s3, s3, s4
	s_sext_i32_i16 s4, s3
	s_bfe_u32 s4, s4, 0x3001c
	v_readlane_b32 s6, v240, 62
	s_add_i32 s4, s3, s4
	s_sext_i32_i16 s6, s4
	s_and_b32 s4, s4, 0xfff8
	s_sub_i32 s3, s3, s4
	v_readlane_b32 s7, v240, 63
	s_sext_i32_i16 s3, s3
	s_mov_b32 s9, s7
	s_lshr_b32 s12, s6, 3
	s_add_i32 s6, s5, s3
	s_ashr_i32 s7, s6, 31
	s_mov_b32 s3, s9
	v_writelane_b32 v240, s2, 62
	s_lshl_b64 s[8:9], s[8:9], 11
	s_lshl_b64 s[4:5], s[6:7], 19
	v_writelane_b32 v240, s3, 63
	s_add_u32 s3, s10, s8
	s_addc_u32 s7, s11, s9
	s_add_u32 s4, s3, s4
	s_mov_b32 vcc_lo, s10
	v_writelane_b32 v238, s11, 3
	s_addc_u32 s5, s7, s5
	s_bfe_i64 s[10:11], s[12:13], 0x100000
	v_lshrrev_b32_e32 v4, 2, v2
	v_lshlrev_b32_e32 v5, 1, v2
	v_and_b32_e32 v1, 0xc0, v1
	s_lshl_b64 s[10:11], s[10:11], 19
	v_and_b32_e32 v4, 4, v4
	v_and_b32_e32 v5, 24, v5
	v_sub_u32_e32 v0, v0, v1
	s_add_u32 s3, s34, s8
	v_or3_b32 v3, v3, v4, v5
	v_lshlrev_b32_e32 v4, 5, v12
	v_ashrrev_i16_sdwa v0, v198, sext(v0) dst_sel:DWORD dst_unused:UNUSED_PAD src0_sel:DWORD src1_sel:BYTE_0
	s_addc_u32 s7, s35, s9
	v_and_b32_e32 v4, 32, v4
	v_bfe_i32 v13, v0, 0, 16
	s_add_u32 s8, s3, s10
	v_add_lshl_u32 v0, v4, v13, 1
	s_addc_u32 s9, s7, s11
	s_add_i32 s10, s13, 0
	v_lshl_add_u32 v164, v3, 11, v0
	s_add_i32 m0, s10, 0x10000
	v_writelane_b32 v238, s34, 11
	global_load_lds_dwordx4 v164, s[8:9]
	s_add_i32 m0, s10, 0x12000
	s_add_u32 s34, s8, 0x40000
	v_writelane_b32 v238, s35, 2
	global_load_lds_dwordx4 v160, s[8:9]
	s_addc_u32 s35, s9, 0
	s_add_i32 m0, s10, 0x14000
	s_add_i32 s11, s10, 0x2000
	global_load_lds_dwordx4 v164, s[34:35]
	s_add_i32 m0, s10, 0x16000
	v_lshl_add_u32 v166, v2, 11, v0
	v_bfe_u32 v228, v166, 11, 6
	v_lshlrev_b32_e32 v229, 2, v228
	v_lshrrev_b32_e32 v228, 4, v228
	v_or_b32_e32 v228, v229, v228
	v_and_b32_e32 v228, 63, v228
	v_and_b32_e32 v166, 0xfffe07ff, v166
	v_lshl_or_b32 v166, v228, 11, v166
	v_bfe_u32 v228, v162, 11, 6
	v_lshlrev_b32_e32 v229, 2, v228
	v_lshrrev_b32_e32 v228, 4, v228
	v_or_b32_e32 v228, v229, v228
	v_and_b32_e32 v228, 63, v228
	v_and_b32_e32 v162, 0xfffe07ff, v162
	v_lshl_or_b32 v162, v228, 11, v162
	global_load_lds_dwordx4 v160, s[34:35]
	s_mov_b32 m0, s10
	s_add_u32 s34, s4, 0x40000
	global_load_lds_dwordx4 v166, s[4:5]
	s_mov_b32 m0, s11
	s_addc_u32 s35, s5, 0
	s_add_i32 s72, s10, 0x4000
	global_load_lds_dwordx4 v162, s[4:5]
	s_mov_b32 m0, s72
	s_add_i32 s73, s10, 0x6000
	global_load_lds_dwordx4 v166, s[34:35]
	s_mov_b32 m0, s73
	v_mov_b32_e32 v161, v165
	global_load_lds_dwordx4 v162, s[34:35]
	v_mov_b32_e32 v167, v165
	v_mov_b32_e32 v163, v165
	s_cmp_eq_u32 s15, 1
	s_mov_b64 s[68:69], s[58:59]
	v_lshl_add_u64 v[6:7], s[8:9], 0, v[164:165]
	v_lshl_add_u64 v[4:5], s[8:9], 0, v[160:161]
	v_lshl_add_u64 v[0:1], s[4:5], 0, v[166:167]
	s_cselect_b64 s[88:89], -1, 0
	s_cmp_lg_u32 s15, 1
	v_lshl_add_u64 v[2:3], s[4:5], 0, v[162:163]
	s_cbranch_scc1 .LBB0_41
	s_barrier
.LBB0_41:
	v_readlane_b32 s34, v239, 29
	v_readlane_b32 s35, v239, 30
	s_add_u32 s90, s34, 0x10100000
	s_sext_i32_i16 s3, s12
	s_addc_u32 s91, s35, 0
	s_mul_i32 s12, s79, 0x10800
	s_mul_hi_i32 s7, s79, 0x10800
	s_waitcnt lgkmcnt(0)
	s_add_u32 s70, s50, s12
	s_addc_u32 s71, s51, s7
	s_mul_i32 s12, s79, 0x5800
	v_readlane_b32 s52, v239, 21
	s_mul_hi_i32 s7, s79, 0x5800
	v_readlane_b32 s53, v239, 22
	s_add_u32 s34, s52, s12
	s_addc_u32 s35, s53, s7
	s_and_b32 s7, s33, 3
	v_and_b32_e32 v14, 48, v211
	v_lshlrev_b32_e32 v15, 6, v211
	s_movk_i32 s33, 0x3c0
	s_lshl_b32 s12, s15, 6
	v_and_or_b32 v14, v15, s33, v14
	v_lshlrev_b32_e32 v15, 2, v211
	v_readlane_b32 s54, v239, 23
	v_readlane_b32 s55, v239, 24
	v_readlane_b32 s56, v239, 25
	v_readlane_b32 s57, v239, 26
	v_readlane_b32 s58, v239, 27
	v_readlane_b32 s59, v239, 28
	v_writelane_b32 v239, s12, 60
	s_lshl_b32 s12, s15, 13
	v_and_b32_e32 v15, 32, v15
	v_bitop3_b32 v16, v14, s12, v15 bitop3:0xde
	s_lshl_b32 s12, s7, 5
	v_writelane_b32 v239, s12, 62
	s_lshl_b32 s12, s7, 12
	s_add_i32 m0, s10, 0x18000
	v_lshl_add_u64 v[6:7], v[6:7], 0, s[0:1]
	v_writelane_b32 v238, s34, 0
	v_bitop3_b32 v188, s12, v14, v15 bitop3:0xf6
	s_waitcnt vmcnt(2)
	s_barrier
	global_load_lds_dwordx4 v[6:7], off
	v_lshl_add_u64 v[4:5], v[4:5], 0, s[0:1]
	s_add_i32 m0, s10, 0x1a000
	s_add_i32 s12, s10, 0x8000
	s_add_i32 s50, s10, 0xa000
	v_writelane_b32 v238, s35, 1
	global_load_lds_dwordx4 v[4:5], off
	v_lshl_add_u64 v[0:1], v[0:1], 0, s[0:1]
	s_mov_b32 m0, s12
	s_add_u32 s34, s8, 0x40080
	global_load_lds_dwordx4 v[0:1], off
	v_lshl_add_u64 v[0:1], v[2:3], 0, s[0:1]
	s_mov_b32 m0, s50
	s_addc_u32 s35, s9, 0
	global_load_lds_dwordx4 v[0:1], off
	s_add_i32 m0, s10, 0x1c000
	v_lshl_add_u64 v[0:1], s[34:35], 0, v[164:165]
	global_load_lds_dwordx4 v[0:1], off
	v_lshl_add_u64 v[0:1], s[34:35], 0, v[160:161]
	s_add_i32 m0, s10, 0x1e000
	s_cmpk_lt_u32 s14, 0x100
	global_load_lds_dwordx4 v[0:1], off
	s_cselect_b64 s[54:55], -1, 0
	s_lshl_b32 s14, s15, 12
	s_lshl_b32 s7, s7, 10
	v_readlane_b32 s34, v240, 59
	v_lshlrev_b32_e32 v0, 14, v8
	s_or_b32 s33, s7, s14
	s_add_i32 s14, s34, s14
	v_and_b32_e32 v0, 0xffff8000, v0
	s_xor_b32 s33, s33, 0x1000
	s_add_i32 s7, s14, s7
	v_lshl_add_u32 v0, v9, 11, v0
	v_and_b32_e32 v1, 1, v8
	s_lshl_b32 s15, s15, 9
	v_writelane_b32 v238, s7, 5
	s_add_i32 s7, s34, s33
	v_lshl_or_b32 v0, v1, 6, v0
	s_add_i32 s7, s7, s15
	v_lshl_add_u32 v168, v10, 1, v0
	v_lshlrev_b32_e32 v0, 14, v12
	s_add_u32 s80, s70, 0x5800
	v_and_b32_e32 v0, 0xffff8000, v0
	s_waitcnt vmcnt(6)
	s_addc_u32 s81, s71, 0
	v_lshl_add_u32 v0, v11, 11, v0
	v_and_b32_e32 v1, 1, v12
	s_add_u32 s86, s70, 0xb000
	v_lshl_or_b32 v0, v1, 6, v0
	s_mov_b64 s[76:77], s[70:71]
	s_addc_u32 s87, s71, 0
	v_mov_b32_e32 v169, v165
	v_lshl_add_u32 v170, v13, 1, v0
	v_bfe_u32 v228, v170, 11, 6
	v_lshlrev_b32_e32 v229, 2, v228
	v_lshrrev_b32_e32 v228, 4, v228
	v_or_b32_e32 v228, v229, v228
	v_and_b32_e32 v228, 63, v228
	v_and_b32_e32 v170, 0xfffe07ff, v170
	v_lshl_or_b32 v170, v228, 11, v170
	v_bfe_u32 v228, v168, 11, 6
	v_lshlrev_b32_e32 v229, 2, v228
	v_lshrrev_b32_e32 v228, 4, v228
	v_or_b32_e32 v228, v229, v228
	v_and_b32_e32 v228, 63, v228
	v_and_b32_e32 v168, 0xfffe07ff, v168
	v_lshl_or_b32 v168, v228, 11, v168
	v_mov_b32_e32 v171, v165
	s_mov_b32 s51, 0
	v_add_u32_e32 v189, 0, v16
	s_mov_b64 s[34:35], s[8:9]
	s_mov_b64 s[14:15], s[4:5]
	s_mov_b64 s[58:59], s[68:69]
	s_mov_b32 s57, vcc_lo
	s_barrier
	v_writelane_b32 v238, s7, 9
	s_branch .LBB0_44

.LBB0_51:
	v_mbcnt_lo_u32_b32 v212, -1, 0
	v_mbcnt_hi_u32_b32 v212, -1, v212
	s_cmp_lt_i32 s6, 16
	s_cselect_b64 vcc, -1, 0
	v_readlane_b32 s4, v238, 0
	v_readlane_b32 s5, v238, 1
	v_lshrrev_b32_e32 v213, 4, v212
	v_and_b32_e32 v212, 15, v212
	s_and_b64 s[52:53], s[88:89], vcc
	s_andn2_b64 s[68:69], vcc, s[88:89]
	v_readlane_b32 s7, v239, 62
	s_lshl_b32 s56, s3, 7
	s_or_b32 s56, s56, s7
	v_lshl_add_u32 v214, v213, 3, s56
	v_lshlrev_b32_e32 v227, 2, v214
	v_add_u32_e32 v236, 0x2c00, v227
	global_load_dwordx4 v[128:131], v227, s[76:77]
	global_load_dwordx4 v[144:147], v236, s[76:77]
	global_load_dwordx4 v[132:135], v227, s[80:81]
	global_load_dwordx4 v[148:151], v236, s[80:81]
	global_load_dwordx4 v[136:139], v227, s[86:87]
	global_load_dwordx4 v[152:155], v236, s[86:87]
	global_load_dwordx4 v[140:143], v227, s[4:5]
	global_load_dwordx4 v[156:159], v236, s[4:5]
	v_readlane_b32 s7, v239, 60
	s_lshl_b32 s3, s6, 8
	s_add_i32 s3, s3, s7
	v_lshl_add_u32 v215, v212, 2, s3
	s_movk_i32 s3, 0x1600
	v_mul_u32_u24_e32 v237, s3, v215
	v_lshl_add_u32 v237, v214, 1, v237
	v_lshlrev_b32_e32 v215, 4, v213
	v_readlane_b32 s7, v238, 9
	s_add_i32 s7, s7, 0xffffff00
	v_add_u32_e32 v226, s7, v215
	v_mov_b32_e32 v220, 0xbfb8aa3b
	v_mov_b32_e32 v221, 0xbfb8aa3b
	v_mov_b32_e32 v222, 1.0
	v_mov_b32_e32 v223, 1.0
	s_cmp_gt_i32 s6, 15
	s_cbranch_scc1 .LUPE_noex
	v_readlane_b32 s7, v238, 5
	s_nop 1
	v_add_u32_e32 v214, s7, v215
	v_cmp_eq_u32_e64 s[6:7], 0, v212
	s_mov_b64 s[8:9], exec
	s_nop 0
	s_and_b64 exec, s[8:9], s[6:7]
	ds_write_b128 v214, v[124:127]
	ds_write_b128 v214, v[60:63] offset:64
	ds_write_b128 v214, v[120:123] offset:128
	ds_write_b128 v214, v[56:59] offset:192
	ds_write_b128 v214, v[92:95] offset:512
	ds_write_b128 v214, v[28:31] offset:576
	ds_write_b128 v214, v[88:91] offset:640
	ds_write_b128 v214, v[24:27] offset:704
	s_mov_b64 exec, s[8:9]
	v_cmp_eq_u32_e64 s[6:7], 15, v212
	s_nop 1
	s_and_b64 exec, s[8:9], s[6:7]
	ds_write_b128 v214, v[100:103] offset:256
	ds_write_b128 v214, v[36:39] offset:320
	ds_write_b128 v214, v[96:99] offset:384
	ds_write_b128 v214, v[32:35] offset:448
	ds_write_b128 v214, v[72:75] offset:768
	ds_write_b128 v214, v[4:7] offset:832
	ds_write_b128 v214, v[64:67] offset:896
	ds_write_b128 v214, v[0:3] offset:960
	s_mov_b64 exec, s[8:9]
	s_waitcnt lgkmcnt(0)
	s_barrier
.LUPE_noex:
	ds_read_b128 v[172:175], v226
	ds_read_b128 v[176:179], v226 offset:128
	ds_read_b128 v[180:183], v226 offset:256
	ds_read_b128 v[184:187], v226 offset:384
	s_waitcnt vmcnt(0) lgkmcnt(0)
	v_cndmask_b32_e64 v172, 0, v172, s[52:53]
	v_cndmask_b32_e64 v173, 0, v173, s[52:53]
	v_cndmask_b32_e64 v174, 0, v174, s[52:53]
	v_cndmask_b32_e64 v175, 0, v175, s[52:53]
	v_cndmask_b32_e64 v176, 0, v176, s[52:53]
	v_cndmask_b32_e64 v177, 0, v177, s[52:53]
	v_cndmask_b32_e64 v178, 0, v178, s[52:53]
	v_cndmask_b32_e64 v179, 0, v179, s[52:53]
	v_cndmask_b32_e32 v180, 0, v180, vcc
	v_cndmask_b32_e32 v181, 0, v181, vcc
	v_cndmask_b32_e32 v182, 0, v182, vcc
	v_cndmask_b32_e32 v183, 0, v183, vcc
	v_cndmask_b32_e32 v184, 0, v184, vcc
	v_cndmask_b32_e32 v185, 0, v185, vcc
	v_cndmask_b32_e32 v186, 0, v186, vcc
	v_cndmask_b32_e32 v187, 0, v187, vcc
	v_pk_fma_f32 v[228:229], v[136:137], v[116:117], v[140:141]
	v_pk_fma_f32 v[230:231], v[138:139], v[118:119], v[142:143]
	v_pk_fma_f32 v[232:233], v[152:153], v[112:113], v[156:157]
	v_pk_fma_f32 v[234:235], v[154:155], v[114:115], v[158:159]
	v_pk_fma_f32 v[228:229], v[132:133], v[124:125], v[228:229]
	v_pk_fma_f32 v[230:231], v[134:135], v[126:127], v[230:231]
	v_pk_fma_f32 v[232:233], v[148:149], v[120:121], v[232:233]
	v_pk_fma_f32 v[234:235], v[150:151], v[122:123], v[234:235]
	v_fmac_f32_dpp v228, v100, v128 row_shr:1 row_mask:0xf bank_mask:0xf bound_ctrl:0
	v_fmac_f32_dpp v229, v101, v129 row_shr:1 row_mask:0xf bank_mask:0xf bound_ctrl:0
	v_fmac_f32_dpp v230, v102, v130 row_shr:1 row_mask:0xf bank_mask:0xf bound_ctrl:0
	v_fmac_f32_dpp v231, v103, v131 row_shr:1 row_mask:0xf bank_mask:0xf bound_ctrl:0
	v_fmac_f32_dpp v232, v96, v144 row_shr:1 row_mask:0xf bank_mask:0xf bound_ctrl:0
	v_fmac_f32_dpp v233, v97, v145 row_shr:1 row_mask:0xf bank_mask:0xf bound_ctrl:0
	v_fmac_f32_dpp v234, v98, v146 row_shr:1 row_mask:0xf bank_mask:0xf bound_ctrl:0
	v_fmac_f32_dpp v235, v99, v147 row_shr:1 row_mask:0xf bank_mask:0xf bound_ctrl:0
	v_fmac_f32_dpp v228, v172, v128 row_shl:15 row_mask:0xf bank_mask:0xf bound_ctrl:0
	v_fmac_f32_dpp v229, v173, v129 row_shl:15 row_mask:0xf bank_mask:0xf bound_ctrl:0
	v_fmac_f32_dpp v230, v174, v130 row_shl:15 row_mask:0xf bank_mask:0xf bound_ctrl:0
	v_fmac_f32_dpp v231, v175, v131 row_shl:15 row_mask:0xf bank_mask:0xf bound_ctrl:0
	v_fmac_f32_dpp v232, v176, v144 row_shl:15 row_mask:0xf bank_mask:0xf bound_ctrl:0
	v_fmac_f32_dpp v233, v177, v145 row_shl:15 row_mask:0xf bank_mask:0xf bound_ctrl:0
	v_fmac_f32_dpp v234, v178, v146 row_shl:15 row_mask:0xf bank_mask:0xf bound_ctrl:0
	v_fmac_f32_dpp v235, v179, v147 row_shl:15 row_mask:0xf bank_mask:0xf bound_ctrl:0
	v_pk_mul_f32 v[216:217], v[228:229], v[220:221]
	v_pk_mul_f32 v[218:219], v[230:231], v[220:221]
	v_exp_f32_e32 v216, v216
	v_exp_f32_e32 v217, v217
	v_exp_f32_e32 v218, v218
	v_exp_f32_e32 v219, v219
	v_pk_add_f32 v[216:217], v[216:217], v[222:223]
	v_pk_add_f32 v[218:219], v[218:219], v[222:223]
	v_rcp_f32_e32 v216, v216
	v_rcp_f32_e32 v217, v217
	v_rcp_f32_e32 v218, v218
	v_rcp_f32_e32 v219, v219
	v_pk_mul_f32 v[228:229], v[228:229], v[216:217]
	v_pk_mul_f32 v[230:231], v[230:231], v[218:219]
	v_pk_mul_f32 v[228:229], v[232:233], v[228:229]
	v_pk_mul_f32 v[230:231], v[234:235], v[230:231]
	s_mov_b64 s[8:9], s[90:91]
	v_cvt_pk_bf16_f32 v224, v228, v229
	v_cvt_pk_bf16_f32 v225, v230, v231
	global_store_dwordx2 v237, v[224:225], s[8:9]
	ds_read_b128 v[172:175], v226 offset:512
	ds_read_b128 v[176:179], v226 offset:640
	v_pk_fma_f32 v[228:229], v[136:137], v[108:109], v[140:141]
	v_pk_fma_f32 v[230:231], v[138:139], v[110:111], v[142:143]
	v_pk_fma_f32 v[232:233], v[152:153], v[104:105], v[156:157]
	v_pk_fma_f32 v[234:235], v[154:155], v[106:107], v[158:159]
	v_pk_fma_f32 v[228:229], v[132:133], v[116:117], v[228:229]
	v_pk_fma_f32 v[230:231], v[134:135], v[118:119], v[230:231]
	v_pk_fma_f32 v[232:233], v[148:149], v[112:113], v[232:233]
	v_pk_fma_f32 v[234:235], v[150:151], v[114:115], v[234:235]
	v_pk_fma_f32 v[228:229], v[128:129], v[124:125], v[228:229]
	v_pk_fma_f32 v[230:231], v[130:131], v[126:127], v[230:231]
	v_pk_fma_f32 v[232:233], v[144:145], v[120:121], v[232:233]
	v_pk_fma_f32 v[234:235], v[146:147], v[122:123], v[234:235]
	v_pk_mul_f32 v[216:217], v[228:229], v[220:221]
	v_pk_mul_f32 v[218:219], v[230:231], v[220:221]
	v_exp_f32_e32 v216, v216
	v_exp_f32_e32 v217, v217
	v_exp_f32_e32 v218, v218
	v_exp_f32_e32 v219, v219
	v_pk_add_f32 v[216:217], v[216:217], v[222:223]
	v_pk_add_f32 v[218:219], v[218:219], v[222:223]
	v_rcp_f32_e32 v216, v216
	v_rcp_f32_e32 v217, v217
	v_rcp_f32_e32 v218, v218
	v_rcp_f32_e32 v219, v219
	v_pk_mul_f32 v[228:229], v[228:229], v[216:217]
	v_pk_mul_f32 v[230:231], v[230:231], v[218:219]
	v_pk_mul_f32 v[228:229], v[232:233], v[228:229]
	v_pk_mul_f32 v[230:231], v[234:235], v[230:231]
	s_add_u32 s8, s90, 0x1600
	s_addc_u32 s9, s91, 0
	v_cvt_pk_bf16_f32 v224, v228, v229
	v_cvt_pk_bf16_f32 v225, v230, v231
	global_store_dwordx2 v237, v[224:225], s[8:9]
	v_pk_fma_f32 v[228:229], v[136:137], v[100:101], v[140:141]
	v_pk_fma_f32 v[230:231], v[138:139], v[102:103], v[142:143]
	v_pk_fma_f32 v[232:233], v[152:153], v[96:97], v[156:157]
	v_pk_fma_f32 v[234:235], v[154:155], v[98:99], v[158:159]
	v_pk_fma_f32 v[228:229], v[132:133], v[108:109], v[228:229]
	v_pk_fma_f32 v[230:231], v[134:135], v[110:111], v[230:231]
	v_pk_fma_f32 v[232:233], v[148:149], v[104:105], v[232:233]
	v_pk_fma_f32 v[234:235], v[150:151], v[106:107], v[234:235]
	v_pk_fma_f32 v[228:229], v[128:129], v[116:117], v[228:229]
	v_pk_fma_f32 v[230:231], v[130:131], v[118:119], v[230:231]
	v_pk_fma_f32 v[232:233], v[144:145], v[112:113], v[232:233]
	v_pk_fma_f32 v[234:235], v[146:147], v[114:115], v[234:235]
	v_pk_mul_f32 v[216:217], v[228:229], v[220:221]
	v_pk_mul_f32 v[218:219], v[230:231], v[220:221]
	v_exp_f32_e32 v216, v216
	v_exp_f32_e32 v217, v217
	v_exp_f32_e32 v218, v218
	v_exp_f32_e32 v219, v219
	v_pk_add_f32 v[216:217], v[216:217], v[222:223]
	v_pk_add_f32 v[218:219], v[218:219], v[222:223]
	v_rcp_f32_e32 v216, v216
	v_rcp_f32_e32 v217, v217
	v_rcp_f32_e32 v218, v218
	v_rcp_f32_e32 v219, v219
	v_pk_mul_f32 v[228:229], v[228:229], v[216:217]
	v_pk_mul_f32 v[230:231], v[230:231], v[218:219]
	v_pk_mul_f32 v[228:229], v[232:233], v[228:229]
	v_pk_mul_f32 v[230:231], v[234:235], v[230:231]
	s_add_u32 s8, s90, 0x2c00
	s_addc_u32 s9, s91, 0
	v_cvt_pk_bf16_f32 v224, v228, v229
	v_cvt_pk_bf16_f32 v225, v230, v231
	global_store_dwordx2 v237, v[224:225], s[8:9]
	v_pk_mov_b32 v[228:229], v[140:141], v[140:141] op_sel:[0,1]
	v_pk_mov_b32 v[230:231], v[142:143], v[142:143] op_sel:[0,1]
	v_pk_mov_b32 v[232:233], v[156:157], v[156:157] op_sel:[0,1]
	v_pk_mov_b32 v[234:235], v[158:159], v[158:159] op_sel:[0,1]
	v_fmac_f32_dpp v228, v124, v136 row_shl:1 row_mask:0xf bank_mask:0xf bound_ctrl:0
	v_fmac_f32_dpp v229, v125, v137 row_shl:1 row_mask:0xf bank_mask:0xf bound_ctrl:0
	v_fmac_f32_dpp v230, v126, v138 row_shl:1 row_mask:0xf bank_mask:0xf bound_ctrl:0
	v_fmac_f32_dpp v231, v127, v139 row_shl:1 row_mask:0xf bank_mask:0xf bound_ctrl:0
	v_fmac_f32_dpp v232, v120, v152 row_shl:1 row_mask:0xf bank_mask:0xf bound_ctrl:0
	v_fmac_f32_dpp v233, v121, v153 row_shl:1 row_mask:0xf bank_mask:0xf bound_ctrl:0
	v_fmac_f32_dpp v234, v122, v154 row_shl:1 row_mask:0xf bank_mask:0xf bound_ctrl:0
	v_fmac_f32_dpp v235, v123, v155 row_shl:1 row_mask:0xf bank_mask:0xf bound_ctrl:0
	v_fmac_f32_dpp v228, v180, v136 row_shr:15 row_mask:0xf bank_mask:0xf bound_ctrl:0
	v_fmac_f32_dpp v229, v181, v137 row_shr:15 row_mask:0xf bank_mask:0xf bound_ctrl:0
	v_fmac_f32_dpp v230, v182, v138 row_shr:15 row_mask:0xf bank_mask:0xf bound_ctrl:0
	v_fmac_f32_dpp v231, v183, v139 row_shr:15 row_mask:0xf bank_mask:0xf bound_ctrl:0
	v_fmac_f32_dpp v232, v184, v152 row_shr:15 row_mask:0xf bank_mask:0xf bound_ctrl:0
	v_fmac_f32_dpp v233, v185, v153 row_shr:15 row_mask:0xf bank_mask:0xf bound_ctrl:0
	v_fmac_f32_dpp v234, v186, v154 row_shr:15 row_mask:0xf bank_mask:0xf bound_ctrl:0
	v_fmac_f32_dpp v235, v187, v155 row_shr:15 row_mask:0xf bank_mask:0xf bound_ctrl:0
	ds_read_b128 v[180:183], v226 offset:768
	ds_read_b128 v[184:187], v226 offset:896
	v_pk_fma_f32 v[228:229], v[132:133], v[100:101], v[228:229]
	v_pk_fma_f32 v[230:231], v[134:135], v[102:103], v[230:231]
	v_pk_fma_f32 v[232:233], v[148:149], v[96:97], v[232:233]
	v_pk_fma_f32 v[234:235], v[150:151], v[98:99], v[234:235]
	v_pk_fma_f32 v[228:229], v[128:129], v[108:109], v[228:229]
	v_pk_fma_f32 v[230:231], v[130:131], v[110:111], v[230:231]
	v_pk_fma_f32 v[232:233], v[144:145], v[104:105], v[232:233]
	v_pk_fma_f32 v[234:235], v[146:147], v[106:107], v[234:235]
	v_pk_mul_f32 v[216:217], v[228:229], v[220:221]
	v_pk_mul_f32 v[218:219], v[230:231], v[220:221]
	v_exp_f32_e32 v216, v216
	v_exp_f32_e32 v217, v217
	v_exp_f32_e32 v218, v218
	v_exp_f32_e32 v219, v219
	v_pk_add_f32 v[216:217], v[216:217], v[222:223]
	v_pk_add_f32 v[218:219], v[218:219], v[222:223]
	v_rcp_f32_e32 v216, v216
	v_rcp_f32_e32 v217, v217
	v_rcp_f32_e32 v218, v218
	v_rcp_f32_e32 v219, v219
	v_pk_mul_f32 v[228:229], v[228:229], v[216:217]
	v_pk_mul_f32 v[230:231], v[230:231], v[218:219]
	v_pk_mul_f32 v[228:229], v[232:233], v[228:229]
	v_pk_mul_f32 v[230:231], v[234:235], v[230:231]
	s_add_u32 s8, s90, 0x4200
	s_addc_u32 s9, s91, 0
	v_cvt_pk_bf16_f32 v224, v228, v229
	v_cvt_pk_bf16_f32 v225, v230, v231
	global_store_dwordx2 v237, v[224:225], s[8:9]
	global_load_dwordx4 v[96:99], v227, s[76:77] offset:16
	global_load_dwordx4 v[112:115], v236, s[76:77] offset:16
	global_load_dwordx4 v[100:103], v227, s[80:81] offset:16
	global_load_dwordx4 v[116:119], v236, s[80:81] offset:16
	global_load_dwordx4 v[104:107], v227, s[86:87] offset:16
	global_load_dwordx4 v[120:123], v236, s[86:87] offset:16
	global_load_dwordx4 v[108:111], v227, s[4:5] offset:16
	global_load_dwordx4 v[124:127], v236, s[4:5] offset:16
	s_waitcnt lgkmcnt(0)
	v_cndmask_b32_e32 v172, 0, v172, vcc
	v_cndmask_b32_e32 v173, 0, v173, vcc
	v_cndmask_b32_e32 v174, 0, v174, vcc
	v_cndmask_b32_e32 v175, 0, v175, vcc
	v_cndmask_b32_e32 v176, 0, v176, vcc
	v_cndmask_b32_e32 v177, 0, v177, vcc
	v_cndmask_b32_e32 v178, 0, v178, vcc
	v_cndmask_b32_e32 v179, 0, v179, vcc
	v_cndmask_b32_e64 v180, 0, v180, s[68:69]
	v_cndmask_b32_e64 v181, 0, v181, s[68:69]
	v_cndmask_b32_e64 v182, 0, v182, s[68:69]
	v_cndmask_b32_e64 v183, 0, v183, s[68:69]
	v_cndmask_b32_e64 v184, 0, v184, s[68:69]
	v_cndmask_b32_e64 v185, 0, v185, s[68:69]
	v_cndmask_b32_e64 v186, 0, v186, s[68:69]
	v_cndmask_b32_e64 v187, 0, v187, s[68:69]
	v_pk_fma_f32 v[228:229], v[136:137], v[84:85], v[140:141]
	v_pk_fma_f32 v[230:231], v[138:139], v[86:87], v[142:143]
	v_pk_fma_f32 v[232:233], v[152:153], v[80:81], v[156:157]
	v_pk_fma_f32 v[234:235], v[154:155], v[82:83], v[158:159]
	v_pk_fma_f32 v[228:229], v[132:133], v[92:93], v[228:229]
	v_pk_fma_f32 v[230:231], v[134:135], v[94:95], v[230:231]
	v_pk_fma_f32 v[232:233], v[148:149], v[88:89], v[232:233]
	v_pk_fma_f32 v[234:235], v[150:151], v[90:91], v[234:235]
	v_fmac_f32_dpp v228, v72, v128 row_shr:1 row_mask:0xf bank_mask:0xf bound_ctrl:0
	v_fmac_f32_dpp v229, v73, v129 row_shr:1 row_mask:0xf bank_mask:0xf bound_ctrl:0
	v_fmac_f32_dpp v230, v74, v130 row_shr:1 row_mask:0xf bank_mask:0xf bound_ctrl:0
	v_fmac_f32_dpp v231, v75, v131 row_shr:1 row_mask:0xf bank_mask:0xf bound_ctrl:0
	v_fmac_f32_dpp v232, v64, v144 row_shr:1 row_mask:0xf bank_mask:0xf bound_ctrl:0
	v_fmac_f32_dpp v233, v65, v145 row_shr:1 row_mask:0xf bank_mask:0xf bound_ctrl:0
	v_fmac_f32_dpp v234, v66, v146 row_shr:1 row_mask:0xf bank_mask:0xf bound_ctrl:0
	v_fmac_f32_dpp v235, v67, v147 row_shr:1 row_mask:0xf bank_mask:0xf bound_ctrl:0
	v_fmac_f32_dpp v228, v172, v128 row_shl:15 row_mask:0xf bank_mask:0xf bound_ctrl:0
	v_fmac_f32_dpp v229, v173, v129 row_shl:15 row_mask:0xf bank_mask:0xf bound_ctrl:0
	v_fmac_f32_dpp v230, v174, v130 row_shl:15 row_mask:0xf bank_mask:0xf bound_ctrl:0
	v_fmac_f32_dpp v231, v175, v131 row_shl:15 row_mask:0xf bank_mask:0xf bound_ctrl:0
	v_fmac_f32_dpp v232, v176, v144 row_shl:15 row_mask:0xf bank_mask:0xf bound_ctrl:0
	v_fmac_f32_dpp v233, v177, v145 row_shl:15 row_mask:0xf bank_mask:0xf bound_ctrl:0
	v_fmac_f32_dpp v234, v178, v146 row_shl:15 row_mask:0xf bank_mask:0xf bound_ctrl:0
	v_fmac_f32_dpp v235, v179, v147 row_shl:15 row_mask:0xf bank_mask:0xf bound_ctrl:0
	v_pk_mul_f32 v[216:217], v[228:229], v[220:221]
	v_pk_mul_f32 v[218:219], v[230:231], v[220:221]
	v_exp_f32_e32 v216, v216
	v_exp_f32_e32 v217, v217
	v_exp_f32_e32 v218, v218
	v_exp_f32_e32 v219, v219
	v_pk_add_f32 v[216:217], v[216:217], v[222:223]
	v_pk_add_f32 v[218:219], v[218:219], v[222:223]
	v_rcp_f32_e32 v216, v216
	v_rcp_f32_e32 v217, v217
	v_rcp_f32_e32 v218, v218
	v_rcp_f32_e32 v219, v219
	v_pk_mul_f32 v[228:229], v[228:229], v[216:217]
	v_pk_mul_f32 v[230:231], v[230:231], v[218:219]
	v_pk_mul_f32 v[228:229], v[232:233], v[228:229]
	v_pk_mul_f32 v[230:231], v[234:235], v[230:231]
	s_add_u32 s8, s90, 0xb0000
	s_addc_u32 s9, s91, 0
	v_cvt_pk_bf16_f32 v224, v228, v229
	v_cvt_pk_bf16_f32 v225, v230, v231
	global_store_dwordx2 v237, v[224:225], s[8:9]
	ds_read_b128 v[172:175], v226 offset:64
	ds_read_b128 v[176:179], v226 offset:192
	v_pk_fma_f32 v[228:229], v[136:137], v[76:77], v[140:141]
	v_pk_fma_f32 v[230:231], v[138:139], v[78:79], v[142:143]
	v_pk_fma_f32 v[232:233], v[152:153], v[68:69], v[156:157]
	v_pk_fma_f32 v[234:235], v[154:155], v[70:71], v[158:159]
	v_pk_fma_f32 v[228:229], v[132:133], v[84:85], v[228:229]
	v_pk_fma_f32 v[230:231], v[134:135], v[86:87], v[230:231]
	v_pk_fma_f32 v[232:233], v[148:149], v[80:81], v[232:233]
	v_pk_fma_f32 v[234:235], v[150:151], v[82:83], v[234:235]
	v_pk_fma_f32 v[228:229], v[128:129], v[92:93], v[228:229]
	v_pk_fma_f32 v[230:231], v[130:131], v[94:95], v[230:231]
	v_pk_fma_f32 v[232:233], v[144:145], v[88:89], v[232:233]
	v_pk_fma_f32 v[234:235], v[146:147], v[90:91], v[234:235]
	v_pk_mul_f32 v[216:217], v[228:229], v[220:221]
	v_pk_mul_f32 v[218:219], v[230:231], v[220:221]
	v_exp_f32_e32 v216, v216
	v_exp_f32_e32 v217, v217
	v_exp_f32_e32 v218, v218
	v_exp_f32_e32 v219, v219
	v_pk_add_f32 v[216:217], v[216:217], v[222:223]
	v_pk_add_f32 v[218:219], v[218:219], v[222:223]
	v_rcp_f32_e32 v216, v216
	v_rcp_f32_e32 v217, v217
	v_rcp_f32_e32 v218, v218
	v_rcp_f32_e32 v219, v219
	v_pk_mul_f32 v[228:229], v[228:229], v[216:217]
	v_pk_mul_f32 v[230:231], v[230:231], v[218:219]
	v_pk_mul_f32 v[228:229], v[232:233], v[228:229]
	v_pk_mul_f32 v[230:231], v[234:235], v[230:231]
	s_add_u32 s8, s90, 0xb1600
	s_addc_u32 s9, s91, 0
	v_cvt_pk_bf16_f32 v224, v228, v229
	v_cvt_pk_bf16_f32 v225, v230, v231
	global_store_dwordx2 v237, v[224:225], s[8:9]
	v_pk_fma_f32 v[228:229], v[136:137], v[72:73], v[140:141]
	v_pk_fma_f32 v[230:231], v[138:139], v[74:75], v[142:143]
	v_pk_fma_f32 v[232:233], v[152:153], v[64:65], v[156:157]
	v_pk_fma_f32 v[234:235], v[154:155], v[66:67], v[158:159]
	v_pk_fma_f32 v[228:229], v[132:133], v[76:77], v[228:229]
	v_pk_fma_f32 v[230:231], v[134:135], v[78:79], v[230:231]
	v_pk_fma_f32 v[232:233], v[148:149], v[68:69], v[232:233]
	v_pk_fma_f32 v[234:235], v[150:151], v[70:71], v[234:235]
	v_pk_fma_f32 v[228:229], v[128:129], v[84:85], v[228:229]
	v_pk_fma_f32 v[230:231], v[130:131], v[86:87], v[230:231]
	v_pk_fma_f32 v[232:233], v[144:145], v[80:81], v[232:233]
	v_pk_fma_f32 v[234:235], v[146:147], v[82:83], v[234:235]
	v_pk_mul_f32 v[216:217], v[228:229], v[220:221]
	v_pk_mul_f32 v[218:219], v[230:231], v[220:221]
	v_exp_f32_e32 v216, v216
	v_exp_f32_e32 v217, v217
	v_exp_f32_e32 v218, v218
	v_exp_f32_e32 v219, v219
	v_pk_add_f32 v[216:217], v[216:217], v[222:223]
	v_pk_add_f32 v[218:219], v[218:219], v[222:223]
	v_rcp_f32_e32 v216, v216
	v_rcp_f32_e32 v217, v217
	v_rcp_f32_e32 v218, v218
	v_rcp_f32_e32 v219, v219
	v_pk_mul_f32 v[228:229], v[228:229], v[216:217]
	v_pk_mul_f32 v[230:231], v[230:231], v[218:219]
	v_pk_mul_f32 v[228:229], v[232:233], v[228:229]
	v_pk_mul_f32 v[230:231], v[234:235], v[230:231]
	s_add_u32 s8, s90, 0xb2c00
	s_addc_u32 s9, s91, 0
	v_cvt_pk_bf16_f32 v224, v228, v229
	v_cvt_pk_bf16_f32 v225, v230, v231
	global_store_dwordx2 v237, v[224:225], s[8:9]
	v_pk_mov_b32 v[228:229], v[140:141], v[140:141] op_sel:[0,1]
	v_pk_mov_b32 v[230:231], v[142:143], v[142:143] op_sel:[0,1]
	v_pk_mov_b32 v[232:233], v[156:157], v[156:157] op_sel:[0,1]
	v_pk_mov_b32 v[234:235], v[158:159], v[158:159] op_sel:[0,1]
	v_fmac_f32_dpp v228, v92, v136 row_shl:1 row_mask:0xf bank_mask:0xf bound_ctrl:0
	v_fmac_f32_dpp v229, v93, v137 row_shl:1 row_mask:0xf bank_mask:0xf bound_ctrl:0
	v_fmac_f32_dpp v230, v94, v138 row_shl:1 row_mask:0xf bank_mask:0xf bound_ctrl:0
	v_fmac_f32_dpp v231, v95, v139 row_shl:1 row_mask:0xf bank_mask:0xf bound_ctrl:0
	v_fmac_f32_dpp v232, v88, v152 row_shl:1 row_mask:0xf bank_mask:0xf bound_ctrl:0
	v_fmac_f32_dpp v233, v89, v153 row_shl:1 row_mask:0xf bank_mask:0xf bound_ctrl:0
	v_fmac_f32_dpp v234, v90, v154 row_shl:1 row_mask:0xf bank_mask:0xf bound_ctrl:0
	v_fmac_f32_dpp v235, v91, v155 row_shl:1 row_mask:0xf bank_mask:0xf bound_ctrl:0
	v_fmac_f32_dpp v228, v180, v136 row_shr:15 row_mask:0xf bank_mask:0xf bound_ctrl:0
	v_fmac_f32_dpp v229, v181, v137 row_shr:15 row_mask:0xf bank_mask:0xf bound_ctrl:0
	v_fmac_f32_dpp v230, v182, v138 row_shr:15 row_mask:0xf bank_mask:0xf bound_ctrl:0
	v_fmac_f32_dpp v231, v183, v139 row_shr:15 row_mask:0xf bank_mask:0xf bound_ctrl:0
	v_fmac_f32_dpp v232, v184, v152 row_shr:15 row_mask:0xf bank_mask:0xf bound_ctrl:0
	v_fmac_f32_dpp v233, v185, v153 row_shr:15 row_mask:0xf bank_mask:0xf bound_ctrl:0
	v_fmac_f32_dpp v234, v186, v154 row_shr:15 row_mask:0xf bank_mask:0xf bound_ctrl:0
	v_fmac_f32_dpp v235, v187, v155 row_shr:15 row_mask:0xf bank_mask:0xf bound_ctrl:0
	ds_read_b128 v[180:183], v226 offset:320
	ds_read_b128 v[184:187], v226 offset:448
	v_pk_fma_f32 v[228:229], v[132:133], v[72:73], v[228:229]
	v_pk_fma_f32 v[230:231], v[134:135], v[74:75], v[230:231]
	v_pk_fma_f32 v[232:233], v[148:149], v[64:65], v[232:233]
	v_pk_fma_f32 v[234:235], v[150:151], v[66:67], v[234:235]
	v_pk_fma_f32 v[228:229], v[128:129], v[76:77], v[228:229]
	v_pk_fma_f32 v[230:231], v[130:131], v[78:79], v[230:231]
	v_pk_fma_f32 v[232:233], v[144:145], v[68:69], v[232:233]
	v_pk_fma_f32 v[234:235], v[146:147], v[70:71], v[234:235]
	v_pk_mul_f32 v[216:217], v[228:229], v[220:221]
	v_pk_mul_f32 v[218:219], v[230:231], v[220:221]
	v_exp_f32_e32 v216, v216
	v_exp_f32_e32 v217, v217
	v_exp_f32_e32 v218, v218
	v_exp_f32_e32 v219, v219
	v_pk_add_f32 v[216:217], v[216:217], v[222:223]
	v_pk_add_f32 v[218:219], v[218:219], v[222:223]
	v_rcp_f32_e32 v216, v216
	v_rcp_f32_e32 v217, v217
	v_rcp_f32_e32 v218, v218
	v_rcp_f32_e32 v219, v219
	v_pk_mul_f32 v[228:229], v[228:229], v[216:217]
	v_pk_mul_f32 v[230:231], v[230:231], v[218:219]
	v_pk_mul_f32 v[228:229], v[232:233], v[228:229]
	v_pk_mul_f32 v[230:231], v[234:235], v[230:231]
	s_add_u32 s8, s90, 0xb4200
	s_addc_u32 s9, s91, 0
	v_cvt_pk_bf16_f32 v224, v228, v229
	v_cvt_pk_bf16_f32 v225, v230, v231
	global_store_dwordx2 v237, v[224:225], s[8:9]
	s_waitcnt vmcnt(4) lgkmcnt(0)
	v_cndmask_b32_e64 v172, 0, v172, s[52:53]
	v_cndmask_b32_e64 v173, 0, v173, s[52:53]
	v_cndmask_b32_e64 v174, 0, v174, s[52:53]
	v_cndmask_b32_e64 v175, 0, v175, s[52:53]
	v_cndmask_b32_e64 v176, 0, v176, s[52:53]
	v_cndmask_b32_e64 v177, 0, v177, s[52:53]
	v_cndmask_b32_e64 v178, 0, v178, s[52:53]
	v_cndmask_b32_e64 v179, 0, v179, s[52:53]
	v_cndmask_b32_e32 v180, 0, v180, vcc
	v_cndmask_b32_e32 v181, 0, v181, vcc
	v_cndmask_b32_e32 v182, 0, v182, vcc
	v_cndmask_b32_e32 v183, 0, v183, vcc
	v_cndmask_b32_e32 v184, 0, v184, vcc
	v_cndmask_b32_e32 v185, 0, v185, vcc
	v_cndmask_b32_e32 v186, 0, v186, vcc
	v_cndmask_b32_e32 v187, 0, v187, vcc
	v_pk_fma_f32 v[228:229], v[104:105], v[52:53], v[108:109]
	v_pk_fma_f32 v[230:231], v[106:107], v[54:55], v[110:111]
	v_pk_fma_f32 v[232:233], v[120:121], v[48:49], v[124:125]
	v_pk_fma_f32 v[234:235], v[122:123], v[50:51], v[126:127]
	v_pk_fma_f32 v[228:229], v[100:101], v[60:61], v[228:229]
	v_pk_fma_f32 v[230:231], v[102:103], v[62:63], v[230:231]
	v_pk_fma_f32 v[232:233], v[116:117], v[56:57], v[232:233]
	v_pk_fma_f32 v[234:235], v[118:119], v[58:59], v[234:235]
	v_fmac_f32_dpp v228, v36, v96 row_shr:1 row_mask:0xf bank_mask:0xf bound_ctrl:0
	v_fmac_f32_dpp v229, v37, v97 row_shr:1 row_mask:0xf bank_mask:0xf bound_ctrl:0
	v_fmac_f32_dpp v230, v38, v98 row_shr:1 row_mask:0xf bank_mask:0xf bound_ctrl:0
	v_fmac_f32_dpp v231, v39, v99 row_shr:1 row_mask:0xf bank_mask:0xf bound_ctrl:0
	v_fmac_f32_dpp v232, v32, v112 row_shr:1 row_mask:0xf bank_mask:0xf bound_ctrl:0
	v_fmac_f32_dpp v233, v33, v113 row_shr:1 row_mask:0xf bank_mask:0xf bound_ctrl:0
	v_fmac_f32_dpp v234, v34, v114 row_shr:1 row_mask:0xf bank_mask:0xf bound_ctrl:0
	v_fmac_f32_dpp v235, v35, v115 row_shr:1 row_mask:0xf bank_mask:0xf bound_ctrl:0
	v_fmac_f32_dpp v228, v172, v96 row_shl:15 row_mask:0xf bank_mask:0xf bound_ctrl:0
	v_fmac_f32_dpp v229, v173, v97 row_shl:15 row_mask:0xf bank_mask:0xf bound_ctrl:0
	v_fmac_f32_dpp v230, v174, v98 row_shl:15 row_mask:0xf bank_mask:0xf bound_ctrl:0
	v_fmac_f32_dpp v231, v175, v99 row_shl:15 row_mask:0xf bank_mask:0xf bound_ctrl:0
	v_fmac_f32_dpp v232, v176, v112 row_shl:15 row_mask:0xf bank_mask:0xf bound_ctrl:0
	v_fmac_f32_dpp v233, v177, v113 row_shl:15 row_mask:0xf bank_mask:0xf bound_ctrl:0
	v_fmac_f32_dpp v234, v178, v114 row_shl:15 row_mask:0xf bank_mask:0xf bound_ctrl:0
	v_fmac_f32_dpp v235, v179, v115 row_shl:15 row_mask:0xf bank_mask:0xf bound_ctrl:0
	v_pk_mul_f32 v[216:217], v[228:229], v[220:221]
	v_pk_mul_f32 v[218:219], v[230:231], v[220:221]
	v_exp_f32_e32 v216, v216
	v_exp_f32_e32 v217, v217
	v_exp_f32_e32 v218, v218
	v_exp_f32_e32 v219, v219
	v_pk_add_f32 v[216:217], v[216:217], v[222:223]
	v_pk_add_f32 v[218:219], v[218:219], v[222:223]
	v_rcp_f32_e32 v216, v216
	v_rcp_f32_e32 v217, v217
	v_rcp_f32_e32 v218, v218
	v_rcp_f32_e32 v219, v219
	v_pk_mul_f32 v[228:229], v[228:229], v[216:217]
	v_pk_mul_f32 v[230:231], v[230:231], v[218:219]
	v_pk_mul_f32 v[228:229], v[232:233], v[228:229]
	v_pk_mul_f32 v[230:231], v[234:235], v[230:231]
	s_mov_b64 s[8:9], s[90:91]
	v_cvt_pk_bf16_f32 v224, v228, v229
	v_cvt_pk_bf16_f32 v225, v230, v231
	global_store_dwordx2 v237, v[224:225], s[8:9] offset:8
	ds_read_b128 v[172:175], v226 offset:576
	ds_read_b128 v[176:179], v226 offset:704
	v_pk_fma_f32 v[228:229], v[104:105], v[44:45], v[108:109]
	v_pk_fma_f32 v[230:231], v[106:107], v[46:47], v[110:111]
	v_pk_fma_f32 v[232:233], v[120:121], v[40:41], v[124:125]
	v_pk_fma_f32 v[234:235], v[122:123], v[42:43], v[126:127]
	v_pk_fma_f32 v[228:229], v[100:101], v[52:53], v[228:229]
	v_pk_fma_f32 v[230:231], v[102:103], v[54:55], v[230:231]
	v_pk_fma_f32 v[232:233], v[116:117], v[48:49], v[232:233]
	v_pk_fma_f32 v[234:235], v[118:119], v[50:51], v[234:235]
	v_pk_fma_f32 v[228:229], v[96:97], v[60:61], v[228:229]
	v_pk_fma_f32 v[230:231], v[98:99], v[62:63], v[230:231]
	v_pk_fma_f32 v[232:233], v[112:113], v[56:57], v[232:233]
	v_pk_fma_f32 v[234:235], v[114:115], v[58:59], v[234:235]
	v_pk_mul_f32 v[216:217], v[228:229], v[220:221]
	v_pk_mul_f32 v[218:219], v[230:231], v[220:221]
	v_exp_f32_e32 v216, v216
	v_exp_f32_e32 v217, v217
	v_exp_f32_e32 v218, v218
	v_exp_f32_e32 v219, v219
	v_pk_add_f32 v[216:217], v[216:217], v[222:223]
	v_pk_add_f32 v[218:219], v[218:219], v[222:223]
	v_rcp_f32_e32 v216, v216
	v_rcp_f32_e32 v217, v217
	v_rcp_f32_e32 v218, v218
	v_rcp_f32_e32 v219, v219
	v_pk_mul_f32 v[228:229], v[228:229], v[216:217]
	v_pk_mul_f32 v[230:231], v[230:231], v[218:219]
	v_pk_mul_f32 v[228:229], v[232:233], v[228:229]
	v_pk_mul_f32 v[230:231], v[234:235], v[230:231]
	s_add_u32 s8, s90, 0x1600
	s_addc_u32 s9, s91, 0
	v_cvt_pk_bf16_f32 v224, v228, v229
	v_cvt_pk_bf16_f32 v225, v230, v231
	global_store_dwordx2 v237, v[224:225], s[8:9] offset:8
	v_pk_fma_f32 v[228:229], v[104:105], v[36:37], v[108:109]
	v_pk_fma_f32 v[230:231], v[106:107], v[38:39], v[110:111]
	v_pk_fma_f32 v[232:233], v[120:121], v[32:33], v[124:125]
	v_pk_fma_f32 v[234:235], v[122:123], v[34:35], v[126:127]
	v_pk_fma_f32 v[228:229], v[100:101], v[44:45], v[228:229]
	v_pk_fma_f32 v[230:231], v[102:103], v[46:47], v[230:231]
	v_pk_fma_f32 v[232:233], v[116:117], v[40:41], v[232:233]
	v_pk_fma_f32 v[234:235], v[118:119], v[42:43], v[234:235]
	v_pk_fma_f32 v[228:229], v[96:97], v[52:53], v[228:229]
	v_pk_fma_f32 v[230:231], v[98:99], v[54:55], v[230:231]
	v_pk_fma_f32 v[232:233], v[112:113], v[48:49], v[232:233]
	v_pk_fma_f32 v[234:235], v[114:115], v[50:51], v[234:235]
	v_pk_mul_f32 v[216:217], v[228:229], v[220:221]
	v_pk_mul_f32 v[218:219], v[230:231], v[220:221]
	v_exp_f32_e32 v216, v216
	v_exp_f32_e32 v217, v217
	v_exp_f32_e32 v218, v218
	v_exp_f32_e32 v219, v219
	v_pk_add_f32 v[216:217], v[216:217], v[222:223]
	v_pk_add_f32 v[218:219], v[218:219], v[222:223]
	v_rcp_f32_e32 v216, v216
	v_rcp_f32_e32 v217, v217
	v_rcp_f32_e32 v218, v218
	v_rcp_f32_e32 v219, v219
	v_pk_mul_f32 v[228:229], v[228:229], v[216:217]
	v_pk_mul_f32 v[230:231], v[230:231], v[218:219]
	v_pk_mul_f32 v[228:229], v[232:233], v[228:229]
	v_pk_mul_f32 v[230:231], v[234:235], v[230:231]
	s_add_u32 s8, s90, 0x2c00
	s_addc_u32 s9, s91, 0
	v_cvt_pk_bf16_f32 v224, v228, v229
	v_cvt_pk_bf16_f32 v225, v230, v231
	global_store_dwordx2 v237, v[224:225], s[8:9] offset:8
	v_pk_mov_b32 v[228:229], v[108:109], v[108:109] op_sel:[0,1]
	v_pk_mov_b32 v[230:231], v[110:111], v[110:111] op_sel:[0,1]
	v_pk_mov_b32 v[232:233], v[124:125], v[124:125] op_sel:[0,1]
	v_pk_mov_b32 v[234:235], v[126:127], v[126:127] op_sel:[0,1]
	v_fmac_f32_dpp v228, v60, v104 row_shl:1 row_mask:0xf bank_mask:0xf bound_ctrl:0
	v_fmac_f32_dpp v229, v61, v105 row_shl:1 row_mask:0xf bank_mask:0xf bound_ctrl:0
	v_fmac_f32_dpp v230, v62, v106 row_shl:1 row_mask:0xf bank_mask:0xf bound_ctrl:0
	v_fmac_f32_dpp v231, v63, v107 row_shl:1 row_mask:0xf bank_mask:0xf bound_ctrl:0
	v_fmac_f32_dpp v232, v56, v120 row_shl:1 row_mask:0xf bank_mask:0xf bound_ctrl:0
	v_fmac_f32_dpp v233, v57, v121 row_shl:1 row_mask:0xf bank_mask:0xf bound_ctrl:0
	v_fmac_f32_dpp v234, v58, v122 row_shl:1 row_mask:0xf bank_mask:0xf bound_ctrl:0
	v_fmac_f32_dpp v235, v59, v123 row_shl:1 row_mask:0xf bank_mask:0xf bound_ctrl:0
	v_fmac_f32_dpp v228, v180, v104 row_shr:15 row_mask:0xf bank_mask:0xf bound_ctrl:0
	v_fmac_f32_dpp v229, v181, v105 row_shr:15 row_mask:0xf bank_mask:0xf bound_ctrl:0
	v_fmac_f32_dpp v230, v182, v106 row_shr:15 row_mask:0xf bank_mask:0xf bound_ctrl:0
	v_fmac_f32_dpp v231, v183, v107 row_shr:15 row_mask:0xf bank_mask:0xf bound_ctrl:0
	v_fmac_f32_dpp v232, v184, v120 row_shr:15 row_mask:0xf bank_mask:0xf bound_ctrl:0
	v_fmac_f32_dpp v233, v185, v121 row_shr:15 row_mask:0xf bank_mask:0xf bound_ctrl:0
	v_fmac_f32_dpp v234, v186, v122 row_shr:15 row_mask:0xf bank_mask:0xf bound_ctrl:0
	v_fmac_f32_dpp v235, v187, v123 row_shr:15 row_mask:0xf bank_mask:0xf bound_ctrl:0
	ds_read_b128 v[180:183], v226 offset:832
	ds_read_b128 v[184:187], v226 offset:960
	v_pk_fma_f32 v[228:229], v[100:101], v[36:37], v[228:229]
	v_pk_fma_f32 v[230:231], v[102:103], v[38:39], v[230:231]
	v_pk_fma_f32 v[232:233], v[116:117], v[32:33], v[232:233]
	v_pk_fma_f32 v[234:235], v[118:119], v[34:35], v[234:235]
	v_pk_fma_f32 v[228:229], v[96:97], v[44:45], v[228:229]
	v_pk_fma_f32 v[230:231], v[98:99], v[46:47], v[230:231]
	v_pk_fma_f32 v[232:233], v[112:113], v[40:41], v[232:233]
	v_pk_fma_f32 v[234:235], v[114:115], v[42:43], v[234:235]
	v_pk_mul_f32 v[216:217], v[228:229], v[220:221]
	v_pk_mul_f32 v[218:219], v[230:231], v[220:221]
	v_exp_f32_e32 v216, v216
	v_exp_f32_e32 v217, v217
	v_exp_f32_e32 v218, v218
	v_exp_f32_e32 v219, v219
	v_pk_add_f32 v[216:217], v[216:217], v[222:223]
	v_pk_add_f32 v[218:219], v[218:219], v[222:223]
	v_rcp_f32_e32 v216, v216
	v_rcp_f32_e32 v217, v217
	v_rcp_f32_e32 v218, v218
	v_rcp_f32_e32 v219, v219
	v_pk_mul_f32 v[228:229], v[228:229], v[216:217]
	v_pk_mul_f32 v[230:231], v[230:231], v[218:219]
	v_pk_mul_f32 v[228:229], v[232:233], v[228:229]
	v_pk_mul_f32 v[230:231], v[234:235], v[230:231]
	s_add_u32 s8, s90, 0x4200
	s_addc_u32 s9, s91, 0
	v_cvt_pk_bf16_f32 v224, v228, v229
	v_cvt_pk_bf16_f32 v225, v230, v231
	global_store_dwordx2 v237, v[224:225], s[8:9] offset:8
	s_waitcnt lgkmcnt(0)
	v_cndmask_b32_e32 v172, 0, v172, vcc
	v_cndmask_b32_e32 v173, 0, v173, vcc
	v_cndmask_b32_e32 v174, 0, v174, vcc
	v_cndmask_b32_e32 v175, 0, v175, vcc
	v_cndmask_b32_e32 v176, 0, v176, vcc
	v_cndmask_b32_e32 v177, 0, v177, vcc
	v_cndmask_b32_e32 v178, 0, v178, vcc
	v_cndmask_b32_e32 v179, 0, v179, vcc
	v_cndmask_b32_e64 v180, 0, v180, s[68:69]
	v_cndmask_b32_e64 v181, 0, v181, s[68:69]
	v_cndmask_b32_e64 v182, 0, v182, s[68:69]
	v_cndmask_b32_e64 v183, 0, v183, s[68:69]
	v_cndmask_b32_e64 v184, 0, v184, s[68:69]
	v_cndmask_b32_e64 v185, 0, v185, s[68:69]
	v_cndmask_b32_e64 v186, 0, v186, s[68:69]
	v_cndmask_b32_e64 v187, 0, v187, s[68:69]
	v_pk_fma_f32 v[228:229], v[104:105], v[20:21], v[108:109]
	v_pk_fma_f32 v[230:231], v[106:107], v[22:23], v[110:111]
	v_pk_fma_f32 v[232:233], v[120:121], v[16:17], v[124:125]
	v_pk_fma_f32 v[234:235], v[122:123], v[18:19], v[126:127]
	v_pk_fma_f32 v[228:229], v[100:101], v[28:29], v[228:229]
	v_pk_fma_f32 v[230:231], v[102:103], v[30:31], v[230:231]
	v_pk_fma_f32 v[232:233], v[116:117], v[24:25], v[232:233]
	v_pk_fma_f32 v[234:235], v[118:119], v[26:27], v[234:235]
	v_fmac_f32_dpp v228, v4, v96 row_shr:1 row_mask:0xf bank_mask:0xf bound_ctrl:0
	v_fmac_f32_dpp v229, v5, v97 row_shr:1 row_mask:0xf bank_mask:0xf bound_ctrl:0
	v_fmac_f32_dpp v230, v6, v98 row_shr:1 row_mask:0xf bank_mask:0xf bound_ctrl:0
	v_fmac_f32_dpp v231, v7, v99 row_shr:1 row_mask:0xf bank_mask:0xf bound_ctrl:0
	v_fmac_f32_dpp v232, v0, v112 row_shr:1 row_mask:0xf bank_mask:0xf bound_ctrl:0
	v_fmac_f32_dpp v233, v1, v113 row_shr:1 row_mask:0xf bank_mask:0xf bound_ctrl:0
	v_fmac_f32_dpp v234, v2, v114 row_shr:1 row_mask:0xf bank_mask:0xf bound_ctrl:0
	v_fmac_f32_dpp v235, v3, v115 row_shr:1 row_mask:0xf bank_mask:0xf bound_ctrl:0
	v_fmac_f32_dpp v228, v172, v96 row_shl:15 row_mask:0xf bank_mask:0xf bound_ctrl:0
	v_fmac_f32_dpp v229, v173, v97 row_shl:15 row_mask:0xf bank_mask:0xf bound_ctrl:0
	v_fmac_f32_dpp v230, v174, v98 row_shl:15 row_mask:0xf bank_mask:0xf bound_ctrl:0
	v_fmac_f32_dpp v231, v175, v99 row_shl:15 row_mask:0xf bank_mask:0xf bound_ctrl:0
	v_fmac_f32_dpp v232, v176, v112 row_shl:15 row_mask:0xf bank_mask:0xf bound_ctrl:0
	v_fmac_f32_dpp v233, v177, v113 row_shl:15 row_mask:0xf bank_mask:0xf bound_ctrl:0
	v_fmac_f32_dpp v234, v178, v114 row_shl:15 row_mask:0xf bank_mask:0xf bound_ctrl:0
	v_fmac_f32_dpp v235, v179, v115 row_shl:15 row_mask:0xf bank_mask:0xf bound_ctrl:0
	v_pk_mul_f32 v[216:217], v[228:229], v[220:221]
	v_pk_mul_f32 v[218:219], v[230:231], v[220:221]
	v_exp_f32_e32 v216, v216
	v_exp_f32_e32 v217, v217
	v_exp_f32_e32 v218, v218
	v_exp_f32_e32 v219, v219
	v_pk_add_f32 v[216:217], v[216:217], v[222:223]
	v_pk_add_f32 v[218:219], v[218:219], v[222:223]
	v_rcp_f32_e32 v216, v216
	v_rcp_f32_e32 v217, v217
	v_rcp_f32_e32 v218, v218
	v_rcp_f32_e32 v219, v219
	v_pk_mul_f32 v[228:229], v[228:229], v[216:217]
	v_pk_mul_f32 v[230:231], v[230:231], v[218:219]
	v_pk_mul_f32 v[228:229], v[232:233], v[228:229]
	v_pk_mul_f32 v[230:231], v[234:235], v[230:231]
	s_add_u32 s8, s90, 0xb0000
	s_addc_u32 s9, s91, 0
	v_cvt_pk_bf16_f32 v224, v228, v229
	v_cvt_pk_bf16_f32 v225, v230, v231
	global_store_dwordx2 v237, v[224:225], s[8:9] offset:8
	v_pk_fma_f32 v[228:229], v[104:105], v[12:13], v[108:109]
	v_pk_fma_f32 v[230:231], v[106:107], v[14:15], v[110:111]
	v_pk_fma_f32 v[232:233], v[120:121], v[8:9], v[124:125]
	v_pk_fma_f32 v[234:235], v[122:123], v[10:11], v[126:127]
	v_pk_fma_f32 v[228:229], v[100:101], v[20:21], v[228:229]
	v_pk_fma_f32 v[230:231], v[102:103], v[22:23], v[230:231]
	v_pk_fma_f32 v[232:233], v[116:117], v[16:17], v[232:233]
	v_pk_fma_f32 v[234:235], v[118:119], v[18:19], v[234:235]
	v_pk_fma_f32 v[228:229], v[96:97], v[28:29], v[228:229]
	v_pk_fma_f32 v[230:231], v[98:99], v[30:31], v[230:231]
	v_pk_fma_f32 v[232:233], v[112:113], v[24:25], v[232:233]
	v_pk_fma_f32 v[234:235], v[114:115], v[26:27], v[234:235]
	v_pk_mul_f32 v[216:217], v[228:229], v[220:221]
	v_pk_mul_f32 v[218:219], v[230:231], v[220:221]
	v_exp_f32_e32 v216, v216
	v_exp_f32_e32 v217, v217
	v_exp_f32_e32 v218, v218
	v_exp_f32_e32 v219, v219
	v_pk_add_f32 v[216:217], v[216:217], v[222:223]
	v_pk_add_f32 v[218:219], v[218:219], v[222:223]
	v_rcp_f32_e32 v216, v216
	v_rcp_f32_e32 v217, v217
	v_rcp_f32_e32 v218, v218
	v_rcp_f32_e32 v219, v219
	v_pk_mul_f32 v[228:229], v[228:229], v[216:217]
	v_pk_mul_f32 v[230:231], v[230:231], v[218:219]
	v_pk_mul_f32 v[228:229], v[232:233], v[228:229]
	v_pk_mul_f32 v[230:231], v[234:235], v[230:231]
	s_add_u32 s8, s90, 0xb1600
	s_addc_u32 s9, s91, 0
	v_cvt_pk_bf16_f32 v224, v228, v229
	v_cvt_pk_bf16_f32 v225, v230, v231
	global_store_dwordx2 v237, v[224:225], s[8:9] offset:8
	v_pk_fma_f32 v[228:229], v[104:105], v[4:5], v[108:109]
	v_pk_fma_f32 v[230:231], v[106:107], v[6:7], v[110:111]
	v_pk_fma_f32 v[232:233], v[120:121], v[0:1], v[124:125]
	v_pk_fma_f32 v[234:235], v[122:123], v[2:3], v[126:127]
	v_pk_fma_f32 v[228:229], v[100:101], v[12:13], v[228:229]
	v_pk_fma_f32 v[230:231], v[102:103], v[14:15], v[230:231]
	v_pk_fma_f32 v[232:233], v[116:117], v[8:9], v[232:233]
	v_pk_fma_f32 v[234:235], v[118:119], v[10:11], v[234:235]
	v_pk_fma_f32 v[228:229], v[96:97], v[20:21], v[228:229]
	v_pk_fma_f32 v[230:231], v[98:99], v[22:23], v[230:231]
	v_pk_fma_f32 v[232:233], v[112:113], v[16:17], v[232:233]
	v_pk_fma_f32 v[234:235], v[114:115], v[18:19], v[234:235]
	v_pk_mul_f32 v[216:217], v[228:229], v[220:221]
	v_pk_mul_f32 v[218:219], v[230:231], v[220:221]
	v_exp_f32_e32 v216, v216
	v_exp_f32_e32 v217, v217
	v_exp_f32_e32 v218, v218
	v_exp_f32_e32 v219, v219
	v_pk_add_f32 v[216:217], v[216:217], v[222:223]
	v_pk_add_f32 v[218:219], v[218:219], v[222:223]
	v_rcp_f32_e32 v216, v216
	v_rcp_f32_e32 v217, v217
	v_rcp_f32_e32 v218, v218
	v_rcp_f32_e32 v219, v219
	v_pk_mul_f32 v[228:229], v[228:229], v[216:217]
	v_pk_mul_f32 v[230:231], v[230:231], v[218:219]
	v_pk_mul_f32 v[228:229], v[232:233], v[228:229]
	v_pk_mul_f32 v[230:231], v[234:235], v[230:231]
	s_add_u32 s8, s90, 0xb2c00
	s_addc_u32 s9, s91, 0
	v_cvt_pk_bf16_f32 v224, v228, v229
	v_cvt_pk_bf16_f32 v225, v230, v231
	global_store_dwordx2 v237, v[224:225], s[8:9] offset:8
	v_pk_mov_b32 v[228:229], v[108:109], v[108:109] op_sel:[0,1]
	v_pk_mov_b32 v[230:231], v[110:111], v[110:111] op_sel:[0,1]
	v_pk_mov_b32 v[232:233], v[124:125], v[124:125] op_sel:[0,1]
	v_pk_mov_b32 v[234:235], v[126:127], v[126:127] op_sel:[0,1]
	v_fmac_f32_dpp v228, v28, v104 row_shl:1 row_mask:0xf bank_mask:0xf bound_ctrl:0
	v_fmac_f32_dpp v229, v29, v105 row_shl:1 row_mask:0xf bank_mask:0xf bound_ctrl:0
	v_fmac_f32_dpp v230, v30, v106 row_shl:1 row_mask:0xf bank_mask:0xf bound_ctrl:0
	v_fmac_f32_dpp v231, v31, v107 row_shl:1 row_mask:0xf bank_mask:0xf bound_ctrl:0
	v_fmac_f32_dpp v232, v24, v120 row_shl:1 row_mask:0xf bank_mask:0xf bound_ctrl:0
	v_fmac_f32_dpp v233, v25, v121 row_shl:1 row_mask:0xf bank_mask:0xf bound_ctrl:0
	v_fmac_f32_dpp v234, v26, v122 row_shl:1 row_mask:0xf bank_mask:0xf bound_ctrl:0
	v_fmac_f32_dpp v235, v27, v123 row_shl:1 row_mask:0xf bank_mask:0xf bound_ctrl:0
	v_fmac_f32_dpp v228, v180, v104 row_shr:15 row_mask:0xf bank_mask:0xf bound_ctrl:0
	v_fmac_f32_dpp v229, v181, v105 row_shr:15 row_mask:0xf bank_mask:0xf bound_ctrl:0
	v_fmac_f32_dpp v230, v182, v106 row_shr:15 row_mask:0xf bank_mask:0xf bound_ctrl:0
	v_fmac_f32_dpp v231, v183, v107 row_shr:15 row_mask:0xf bank_mask:0xf bound_ctrl:0
	v_fmac_f32_dpp v232, v184, v120 row_shr:15 row_mask:0xf bank_mask:0xf bound_ctrl:0
	v_fmac_f32_dpp v233, v185, v121 row_shr:15 row_mask:0xf bank_mask:0xf bound_ctrl:0
	v_fmac_f32_dpp v234, v186, v122 row_shr:15 row_mask:0xf bank_mask:0xf bound_ctrl:0
	v_fmac_f32_dpp v235, v187, v123 row_shr:15 row_mask:0xf bank_mask:0xf bound_ctrl:0
	v_pk_fma_f32 v[228:229], v[100:101], v[4:5], v[228:229]
	v_pk_fma_f32 v[230:231], v[102:103], v[6:7], v[230:231]
	v_pk_fma_f32 v[232:233], v[116:117], v[0:1], v[232:233]
	v_pk_fma_f32 v[234:235], v[118:119], v[2:3], v[234:235]
	v_pk_fma_f32 v[228:229], v[96:97], v[12:13], v[228:229]
	v_pk_fma_f32 v[230:231], v[98:99], v[14:15], v[230:231]
	v_pk_fma_f32 v[232:233], v[112:113], v[8:9], v[232:233]
	v_pk_fma_f32 v[234:235], v[114:115], v[10:11], v[234:235]
	v_pk_mul_f32 v[216:217], v[228:229], v[220:221]
	v_pk_mul_f32 v[218:219], v[230:231], v[220:221]
	v_exp_f32_e32 v216, v216
	v_exp_f32_e32 v217, v217
	v_exp_f32_e32 v218, v218
	v_exp_f32_e32 v219, v219
	v_pk_add_f32 v[216:217], v[216:217], v[222:223]
	v_pk_add_f32 v[218:219], v[218:219], v[222:223]
	v_rcp_f32_e32 v216, v216
	v_rcp_f32_e32 v217, v217
	v_rcp_f32_e32 v218, v218
	v_rcp_f32_e32 v219, v219
	v_pk_mul_f32 v[228:229], v[228:229], v[216:217]
	v_pk_mul_f32 v[230:231], v[230:231], v[218:219]
	v_pk_mul_f32 v[228:229], v[232:233], v[228:229]
	v_pk_mul_f32 v[230:231], v[234:235], v[230:231]
	s_add_u32 s8, s90, 0xb4200
	s_addc_u32 s9, s91, 0
	v_cvt_pk_bf16_f32 v224, v228, v229
	v_cvt_pk_bf16_f32 v225, v230, v231
	global_store_dwordx2 v237, v[224:225], s[8:9] offset:8
	s_andn2_b64 vcc, exec, s[82:83]
	s_mov_b64 s[4:5], -1
	s_cbranch_vccnz .LBB0_43
	s_andn2_b64 vcc, exec, s[88:89]
	s_cbranch_vccnz .LBB0_42
	s_barrier
	s_branch .LBB0_42

.LBB0_70:
	s_lshl_b32 s8, s11, 6
	v_or_b32_e32 v21, s8, v1
	v_mov_b64_e32 v[6:7], s[6:7]
	s_movk_i32 s9, 0x5800
	v_mad_i64_i32 v[6:7], s[50:51], v21, s9, v[6:7]
	s_ashr_i32 s11, s10, 31
	v_lshl_add_u64 v[6:7], s[10:11], 2, v[6:7]
	v_lshl_add_u64 v[6:7], v[6:7], 0, v[164:165]
	v_add_co_u32_e32 v22, vcc, 0xb000, v6
	s_mov_b32 s9, 0x16000
	s_nop 0
	v_addc_co_u32_e32 v23, vcc, 0, v7, vcc
	global_load_dword v21, v[6:7], off nt
	global_load_dword v24, v[22:23], off nt
	v_add_co_u32_e32 v22, vcc, s9, v6
	s_mov_b32 s9, 0x2c000
	s_nop 0
	v_addc_co_u32_e32 v23, vcc, 0, v7, vcc
	global_load_dword v25, v[22:23], off nt
	v_add_co_u32_e32 v22, vcc, 0x21000, v6
	s_nop 1
	v_addc_co_u32_e32 v23, vcc, 0, v7, vcc
	global_load_dword v26, v[22:23], off nt
	v_add_co_u32_e32 v22, vcc, s9, v6
	s_mov_b32 s9, 0xb0000
	s_nop 0
	v_addc_co_u32_e32 v23, vcc, 0, v7, vcc
	global_load_dword v27, v[22:23], off nt
	v_add_co_u32_e32 v22, vcc, 0x37000, v6
	s_nop 1
	v_addc_co_u32_e32 v23, vcc, 0, v7, vcc
	global_load_dword v28, v[22:23], off nt
	v_add_co_u32_e32 v22, vcc, s63, v6
	s_nop 1
	v_addc_co_u32_e32 v23, vcc, 0, v7, vcc
	global_load_dword v29, v[22:23], off nt
	v_add_co_u32_e32 v22, vcc, 0x4d000, v6
	s_nop 1
	v_addc_co_u32_e32 v23, vcc, 0, v7, vcc
	global_load_dword v30, v[22:23], off nt
	v_add_co_u32_e32 v22, vcc, 0x58000, v6
	s_nop 1
	v_addc_co_u32_e32 v23, vcc, 0, v7, vcc
	global_load_dword v31, v[22:23], off nt
	v_add_co_u32_e32 v22, vcc, 0x63000, v6
	s_nop 1
	v_addc_co_u32_e32 v23, vcc, 0, v7, vcc
	global_load_dword v32, v[22:23], off nt
	v_add_co_u32_e32 v22, vcc, 0x6e000, v6
	s_nop 1
	v_addc_co_u32_e32 v23, vcc, 0, v7, vcc
	global_load_dword v33, v[22:23], off nt
	v_add_co_u32_e32 v22, vcc, 0x79000, v6
	s_nop 1
	v_addc_co_u32_e32 v23, vcc, 0, v7, vcc
	global_load_dword v34, v[22:23], off nt
	v_add_co_u32_e32 v22, vcc, 0x84000, v6
	s_nop 1
	v_addc_co_u32_e32 v23, vcc, 0, v7, vcc
	global_load_dword v35, v[22:23], off nt
	v_add_co_u32_e32 v22, vcc, 0x8f000, v6
	s_nop 1
	v_addc_co_u32_e32 v23, vcc, 0, v7, vcc
	global_load_dword v36, v[22:23], off nt
	v_add_co_u32_e32 v22, vcc, 0x9a000, v6
	s_nop 1
	v_addc_co_u32_e32 v23, vcc, 0, v7, vcc
	global_load_dword v37, v[22:23], off nt
	v_add_co_u32_e32 v22, vcc, 0xa5000, v6
	s_nop 1
	v_addc_co_u32_e32 v23, vcc, 0, v7, vcc
	global_load_dword v38, v[22:23], off nt
	v_add_co_u32_e32 v22, vcc, s9, v6
	s_mov_b32 s9, 0xc6000
	s_nop 0
	v_addc_co_u32_e32 v23, vcc, 0, v7, vcc
	global_load_dword v39, v[22:23], off nt
	v_add_co_u32_e32 v22, vcc, 0xbb000, v6
	s_nop 1
	v_addc_co_u32_e32 v23, vcc, 0, v7, vcc
	global_load_dword v40, v[22:23], off nt
	v_add_co_u32_e32 v22, vcc, s9, v6
	s_mov_b32 s9, 0xdc000
	s_nop 0
	v_addc_co_u32_e32 v23, vcc, 0, v7, vcc
	global_load_dword v41, v[22:23], off nt
	v_add_co_u32_e32 v22, vcc, 0xd1000, v6
	s_nop 1
	v_addc_co_u32_e32 v23, vcc, 0, v7, vcc
	global_load_dword v42, v[22:23], off nt
	v_add_co_u32_e32 v22, vcc, s9, v6
	s_mov_b32 s9, 0xf2000
	s_nop 0
	v_addc_co_u32_e32 v23, vcc, 0, v7, vcc
	global_load_dword v43, v[22:23], off nt
	v_add_co_u32_e32 v22, vcc, 0xe7000, v6
	s_nop 1
	v_addc_co_u32_e32 v23, vcc, 0, v7, vcc
	global_load_dword v44, v[22:23], off nt
	v_add_co_u32_e32 v22, vcc, s9, v6
	s_ashr_i32 s9, s8, 31
	s_nop 0
	v_addc_co_u32_e32 v23, vcc, 0, v7, vcc
	global_load_dword v45, v[22:23], off nt
	v_add_co_u32_e32 v22, vcc, 0xfd000, v6
	s_nop 1
	v_addc_co_u32_e32 v23, vcc, 0, v7, vcc
	global_load_dword v46, v[22:23], off nt
	v_add_co_u32_e32 v22, vcc, 0x108000, v6
	s_nop 1
	v_addc_co_u32_e32 v23, vcc, 0, v7, vcc
	global_load_dword v47, v[22:23], off nt
	v_add_co_u32_e32 v22, vcc, 0x113000, v6
	s_nop 1
	v_addc_co_u32_e32 v23, vcc, 0, v7, vcc
	global_load_dword v48, v[22:23], off nt
	v_add_co_u32_e32 v22, vcc, 0x11e000, v6
	s_nop 1
	v_addc_co_u32_e32 v23, vcc, 0, v7, vcc
	global_load_dword v49, v[22:23], off nt
	v_add_co_u32_e32 v22, vcc, 0x129000, v6
	s_nop 1
	v_addc_co_u32_e32 v23, vcc, 0, v7, vcc
	global_load_dword v50, v[22:23], off nt
	v_add_co_u32_e32 v22, vcc, 0x134000, v6
	s_nop 1
	v_addc_co_u32_e32 v23, vcc, 0, v7, vcc
	global_load_dword v51, v[22:23], off nt
	v_add_co_u32_e32 v22, vcc, 0x13f000, v6
	s_nop 1
	v_addc_co_u32_e32 v23, vcc, 0, v7, vcc
	global_load_dword v52, v[22:23], off nt
	v_add_co_u32_e32 v22, vcc, 0x14a000, v6
	s_nop 1
	v_addc_co_u32_e32 v23, vcc, 0, v7, vcc
	v_add_co_u32_e32 v6, vcc, 0x155000, v6
	global_load_dword v22, v[22:23], off nt
	s_nop 0
	v_addc_co_u32_e32 v7, vcc, 0, v7, vcc
	global_load_dword v6, v[6:7], off nt
	s_waitcnt vmcnt(0)
	ds_write2_b32 v13, v21, v24 offset1:66
	ds_write2_b32 v13, v25, v26 offset0:132 offset1:198
	ds_write2_b32 v20, v27, v28 offset0:8 offset1:74
	ds_write2_b32 v20, v29, v30 offset0:140 offset1:206
	ds_write2_b32 v19, v31, v32 offset0:16 offset1:82
	ds_write2_b32 v19, v33, v34 offset0:148 offset1:214
	ds_write2_b32 v18, v35, v36 offset0:24 offset1:90
	ds_write2_b32 v18, v37, v38 offset0:156 offset1:222
	ds_write2_b32 v17, v39, v40 offset0:32 offset1:98
	ds_write2_b32 v17, v41, v42 offset0:164 offset1:230
	ds_write2_b32 v16, v43, v44 offset0:40 offset1:106
	ds_write2_b32 v16, v45, v46 offset0:172 offset1:238
	ds_write2_b32 v15, v47, v48 offset0:48 offset1:114
	ds_write2_b32 v15, v49, v50 offset0:180 offset1:246
	ds_write2_b32 v14, v51, v52 offset0:56 offset1:122
	ds_write2_b32 v14, v22, v6 offset0:188 offset1:254
	s_waitcnt lgkmcnt(0)
	ds_read_b32 v60, v9
	ds_read_b32 v61, v9 offset:132
	ds_read_b32 v62, v9 offset:264
	ds_read_b32 v63, v9 offset:396
	ds_read_b32 v64, v9 offset:528
	ds_read_b32 v65, v9 offset:660
	ds_read_b32 v66, v9 offset:792
	ds_read_b32 v67, v9 offset:924
	ds_read_b32 v68, v9 offset:32
	ds_read_b32 v69, v9 offset:164
	ds_read_b32 v70, v9 offset:296
	ds_read_b32 v71, v9 offset:428
	ds_read_b32 v72, v9 offset:560
	ds_read_b32 v73, v9 offset:692
	ds_read_b32 v74, v9 offset:824
	ds_read_b32 v75, v9 offset:956
	s_waitcnt lgkmcnt(8)
	v_cvt_pk_bf16_f32 v14, v60, v61
	v_cvt_pk_bf16_f32 v15, v62, v63
	v_cvt_pk_bf16_f32 v16, v64, v65
	v_cvt_pk_bf16_f32 v17, v66, v67
	ds_read_b32 v76, v9 offset:64
	ds_read_b32 v77, v9 offset:196
	ds_read_b32 v78, v9 offset:328
	ds_read_b32 v79, v9 offset:460
	ds_read_b32 v80, v9 offset:592
	ds_read_b32 v81, v9 offset:724
	ds_read_b32 v82, v9 offset:856
	ds_read_b32 v83, v9 offset:988
	v_add_u32_e32 v18, s35, v8
	v_ashrrev_i32_e32 v19, 31, v18
	v_lshl_add_u64 v[6:7], s[8:9], 1, v[4:5]
	v_lshlrev_b64 v[18:19], 11, v[18:19]
	v_lshl_add_u64 v[18:19], v[6:7], 0, v[18:19]
	global_store_dwordx4 v[18:19], v[14:17], off
	s_nop 1
	s_waitcnt lgkmcnt(8)
	v_cvt_pk_bf16_f32 v14, v68, v69
	v_cvt_pk_bf16_f32 v15, v70, v71
	v_cvt_pk_bf16_f32 v16, v72, v73
	v_cvt_pk_bf16_f32 v17, v74, v75
	ds_read_b32 v84, v9 offset:96
	ds_read_b32 v85, v9 offset:228
	ds_read_b32 v86, v9 offset:360
	ds_read_b32 v87, v9 offset:492
	ds_read_b32 v88, v9 offset:624
	ds_read_b32 v89, v9 offset:756
	ds_read_b32 v90, v9 offset:888
	ds_read_b32 v91, v9 offset:1020
	v_add_u32_e32 v18, s35, v10
	v_ashrrev_i32_e32 v19, 31, v18
	v_lshlrev_b64 v[18:19], 11, v[18:19]
	v_lshl_add_u64 v[18:19], v[6:7], 0, v[18:19]
	global_store_dwordx4 v[18:19], v[14:17], off
	s_nop 1
	s_waitcnt lgkmcnt(8)
	v_cvt_pk_bf16_f32 v14, v76, v77
	v_cvt_pk_bf16_f32 v15, v78, v79
	v_cvt_pk_bf16_f32 v16, v80, v81
	v_cvt_pk_bf16_f32 v17, v82, v83
	v_add_u32_e32 v18, s35, v11
	v_ashrrev_i32_e32 v19, 31, v18
	v_lshlrev_b64 v[18:19], 11, v[18:19]
	v_lshl_add_u64 v[18:19], v[6:7], 0, v[18:19]
	global_store_dwordx4 v[18:19], v[14:17], off
	s_nop 1
	s_waitcnt lgkmcnt(0)
	v_cvt_pk_bf16_f32 v14, v84, v85
	v_cvt_pk_bf16_f32 v15, v86, v87
	v_cvt_pk_bf16_f32 v16, v88, v89
	v_cvt_pk_bf16_f32 v17, v90, v91
	v_add_u32_e32 v18, s35, v12
	v_ashrrev_i32_e32 v19, 31, v18
	v_lshlrev_b64 v[18:19], 11, v[18:19]
	v_lshl_add_u64 v[6:7], v[6:7], 0, v[18:19]
	global_store_dwordx4 v[6:7], v[14:17], off
	s_nop 1
	s_waitcnt lgkmcnt(0)

.LBB0_72:
	s_mov_b64 s[8:9], -1
	s_cmpk_gt_i32 s3, 0xaff
	v_lshlrev_b32_e32 v164, 2, v0
	v_add_u32_e32 v20, 0x400, v13
	v_add_u32_e32 v19, 0x800, v13
	v_add_u32_e32 v18, 0xc00, v13
	v_add_u32_e32 v17, 0x1000, v13
	v_add_u32_e32 v16, 0x1400, v13
	v_add_u32_e32 v15, 0x1800, v13
	v_add_u32_e32 v14, 0x1c00, v13
	s_cbranch_scc0 .LBB0_74
	s_and_b32 s9, s33, 0x1ffc0
	v_or_b32_e32 v6, s9, v1
	s_and_b32 s8, s12, 0x3e0
	v_lshlrev_b32_e32 v6, 12, v6
	v_mov_b32_e32 v7, v165
	v_readlane_b32 s10, v240, 62
	v_lshl_add_u64 v[6:7], s[4:5], 0, v[6:7]
	v_readlane_b32 s11, v240, 63
	s_lshl_b32 s10, s8, 2
	s_nop 0
	v_lshl_add_u64 v[6:7], v[6:7], 0, s[10:11]
	v_lshl_add_u64 v[6:7], v[6:7], 0, v[164:165]
	v_add_co_u32_e32 v22, vcc, 0x2000, v6
	global_load_dword v21, v[6:7], off nt
	s_nop 0
	v_addc_co_u32_e32 v23, vcc, 0, v7, vcc
	global_load_dword v24, v[22:23], off nt
	v_add_co_u32_e32 v22, vcc, 0x4000, v6
	s_mov_b32 s10, 0x10000
	s_nop 0
	v_addc_co_u32_e32 v23, vcc, 0, v7, vcc
	global_load_dword v25, v[22:23], off nt
	v_add_co_u32_e32 v22, vcc, 0x6000, v6
	s_nop 1
	v_addc_co_u32_e32 v23, vcc, 0, v7, vcc
	global_load_dword v26, v[22:23], off nt
	v_add_co_u32_e32 v22, vcc, 0x8000, v6
	s_nop 1
	v_addc_co_u32_e32 v23, vcc, 0, v7, vcc
	global_load_dword v27, v[22:23], off nt
	v_add_co_u32_e32 v22, vcc, 0xa000, v6
	s_nop 1
	v_addc_co_u32_e32 v23, vcc, 0, v7, vcc
	global_load_dword v28, v[22:23], off nt
	v_add_co_u32_e32 v22, vcc, 0xc000, v6
	s_nop 1
	v_addc_co_u32_e32 v23, vcc, 0, v7, vcc
	global_load_dword v29, v[22:23], off nt
	v_add_co_u32_e32 v22, vcc, 0xe000, v6
	s_nop 1
	v_addc_co_u32_e32 v23, vcc, 0, v7, vcc
	global_load_dword v30, v[22:23], off nt
	v_add_co_u32_e32 v22, vcc, s10, v6
	s_mov_b32 s10, 0x14000
	s_nop 0
	v_addc_co_u32_e32 v23, vcc, 0, v7, vcc
	global_load_dword v31, v[22:23], off nt
	v_add_co_u32_e32 v22, vcc, s62, v6
	s_nop 1
	v_addc_co_u32_e32 v23, vcc, 0, v7, vcc
	global_load_dword v32, v[22:23], off nt
	v_add_co_u32_e32 v22, vcc, s10, v6
	s_mov_b32 s10, 0x16000
	s_nop 0
	v_addc_co_u32_e32 v23, vcc, 0, v7, vcc
	global_load_dword v33, v[22:23], off nt
	v_add_co_u32_e32 v22, vcc, s10, v6
	s_mov_b32 s10, 0x1a000
	s_nop 0
	v_addc_co_u32_e32 v23, vcc, 0, v7, vcc
	global_load_dword v34, v[22:23], off nt
	v_add_co_u32_e32 v22, vcc, s75, v6
	s_nop 1
	v_addc_co_u32_e32 v23, vcc, 0, v7, vcc
	global_load_dword v35, v[22:23], off nt
	v_add_co_u32_e32 v22, vcc, s10, v6
	s_mov_b32 s10, 0x1c000
	s_nop 0
	v_addc_co_u32_e32 v23, vcc, 0, v7, vcc
	global_load_dword v36, v[22:23], off nt
	v_add_co_u32_e32 v22, vcc, s10, v6
	s_mov_b32 s10, 0x20000
	s_nop 0
	v_addc_co_u32_e32 v23, vcc, 0, v7, vcc
	global_load_dword v37, v[22:23], off nt
	v_add_co_u32_e32 v22, vcc, s94, v6
	s_nop 1
	v_addc_co_u32_e32 v23, vcc, 0, v7, vcc
	global_load_dword v38, v[22:23], off nt
	v_add_co_u32_e32 v22, vcc, s10, v6
	s_mov_b32 s10, 0x22000
	s_nop 0
	v_addc_co_u32_e32 v23, vcc, 0, v7, vcc
	global_load_dword v39, v[22:23], off nt
	v_add_co_u32_e32 v22, vcc, s10, v6
	s_mov_b32 s10, 0x26000
	s_nop 0
	v_addc_co_u32_e32 v23, vcc, 0, v7, vcc
	global_load_dword v40, v[22:23], off nt
	v_add_co_u32_e32 v22, vcc, s92, v6
	s_nop 1
	v_addc_co_u32_e32 v23, vcc, 0, v7, vcc
	global_load_dword v41, v[22:23], off nt
	v_add_co_u32_e32 v22, vcc, s10, v6
	s_mov_b32 s10, 0x28000
	s_nop 0
	v_addc_co_u32_e32 v23, vcc, 0, v7, vcc
	global_load_dword v42, v[22:23], off nt
	v_add_co_u32_e32 v22, vcc, s10, v6
	s_mov_b32 s10, 0x2c000
	s_nop 0
	v_addc_co_u32_e32 v23, vcc, 0, v7, vcc
	global_load_dword v43, v[22:23], off nt
	v_add_co_u32_e32 v22, vcc, s52, v6
	s_nop 1
	v_addc_co_u32_e32 v23, vcc, 0, v7, vcc
	global_load_dword v44, v[22:23], off nt
	v_add_co_u32_e32 v22, vcc, s10, v6
	s_mov_b32 s10, 0x2e000
	s_nop 0
	v_addc_co_u32_e32 v23, vcc, 0, v7, vcc
	global_load_dword v45, v[22:23], off nt
	v_add_co_u32_e32 v22, vcc, s10, v6
	s_mov_b32 s10, 0x32000
	s_nop 0
	v_addc_co_u32_e32 v23, vcc, 0, v7, vcc
	global_load_dword v46, v[22:23], off nt
	v_add_co_u32_e32 v22, vcc, s2, v6
	s_nop 1
	v_addc_co_u32_e32 v23, vcc, 0, v7, vcc
	global_load_dword v47, v[22:23], off nt
	v_add_co_u32_e32 v22, vcc, s10, v6
	s_mov_b32 s10, 0x34000
	s_nop 0
	v_addc_co_u32_e32 v23, vcc, 0, v7, vcc
	global_load_dword v48, v[22:23], off nt
	v_add_co_u32_e32 v22, vcc, s10, v6
	s_mov_b32 s10, 0x38000
	s_nop 0
	v_addc_co_u32_e32 v23, vcc, 0, v7, vcc
	global_load_dword v49, v[22:23], off nt
	v_add_co_u32_e32 v22, vcc, s53, v6
	s_nop 1
	v_addc_co_u32_e32 v23, vcc, 0, v7, vcc
	global_load_dword v50, v[22:23], off nt
	v_add_co_u32_e32 v22, vcc, s10, v6
	s_mov_b32 s10, 0x3a000
	s_nop 0
	v_addc_co_u32_e32 v23, vcc, 0, v7, vcc
	global_load_dword v51, v[22:23], off nt
	v_add_co_u32_e32 v22, vcc, s10, v6
	s_mov_b32 s10, 0x3e000
	s_nop 0
	v_addc_co_u32_e32 v23, vcc, 0, v7, vcc
	global_load_dword v52, v[22:23], off nt
	v_add_co_u32_e32 v22, vcc, s93, v6
	s_nop 1
	v_addc_co_u32_e32 v23, vcc, 0, v7, vcc
	v_add_co_u32_e32 v6, vcc, s10, v6
	global_load_dword v22, v[22:23], off nt
	s_nop 0
	v_addc_co_u32_e32 v7, vcc, 0, v7, vcc
	global_load_dword v6, v[6:7], off nt
	s_waitcnt vmcnt(0)
	ds_write2_b32 v13, v21, v24 offset1:66
	ds_write2_b32 v13, v25, v26 offset0:132 offset1:198
	ds_write2_b32 v20, v27, v28 offset0:8 offset1:74
	ds_write2_b32 v20, v29, v30 offset0:140 offset1:206
	ds_write2_b32 v19, v31, v32 offset0:16 offset1:82
	ds_write2_b32 v19, v33, v34 offset0:148 offset1:214
	ds_write2_b32 v18, v35, v36 offset0:24 offset1:90
	ds_write2_b32 v18, v37, v38 offset0:156 offset1:222
	ds_write2_b32 v17, v39, v40 offset0:32 offset1:98
	ds_write2_b32 v17, v41, v42 offset0:164 offset1:230
	ds_write2_b32 v16, v43, v44 offset0:40 offset1:106
	ds_write2_b32 v16, v45, v46 offset0:172 offset1:238
	ds_write2_b32 v15, v47, v48 offset0:48 offset1:114
	ds_write2_b32 v15, v49, v50 offset0:180 offset1:246
	ds_write2_b32 v14, v51, v52 offset0:56 offset1:122
	ds_write2_b32 v14, v22, v6 offset0:188 offset1:254
	s_waitcnt lgkmcnt(0)
	ds_read_b32 v60, v9
	ds_read_b32 v61, v9 offset:132
	ds_read_b32 v62, v9 offset:264
	ds_read_b32 v63, v9 offset:396
	ds_read_b32 v64, v9 offset:528
	ds_read_b32 v65, v9 offset:660
	ds_read_b32 v66, v9 offset:792
	ds_read_b32 v67, v9 offset:924
	ds_read_b32 v68, v9 offset:32
	ds_read_b32 v69, v9 offset:164
	ds_read_b32 v70, v9 offset:296
	ds_read_b32 v71, v9 offset:428
	ds_read_b32 v72, v9 offset:560
	ds_read_b32 v73, v9 offset:692
	ds_read_b32 v74, v9 offset:824
	ds_read_b32 v75, v9 offset:956
	s_waitcnt lgkmcnt(8)
	v_cvt_pk_bf16_f32 v22, v60, v61
	v_cvt_pk_bf16_f32 v23, v62, v63
	v_cvt_pk_bf16_f32 v24, v64, v65
	s_lshl_b32 s10, s9, 1
	s_mov_b32 s9, s11
	v_writelane_b32 v240, s8, 62
	v_cvt_pk_bf16_f32 v25, v66, v67
	ds_read_b32 v76, v9 offset:64
	ds_read_b32 v77, v9 offset:196
	ds_read_b32 v78, v9 offset:328
	ds_read_b32 v79, v9 offset:460
	ds_read_b32 v80, v9 offset:592
	ds_read_b32 v81, v9 offset:724
	ds_read_b32 v82, v9 offset:856
	ds_read_b32 v83, v9 offset:988
	v_lshl_add_u64 v[6:7], v[2:3], 0, s[10:11]
	v_or_b32_e32 v21, s8, v8
	v_mul_u32_u24_e32 v21, 0xb00, v21
	v_lshlrev_b32_e32 v26, 1, v21
	v_mov_b32_e32 v27, v165
	v_lshl_add_u64 v[26:27], v[6:7], 0, v[26:27]
	global_store_dwordx4 v[26:27], v[22:25], off
	s_nop 1
	s_waitcnt lgkmcnt(8)
	v_cvt_pk_bf16_f32 v22, v68, v69
	v_cvt_pk_bf16_f32 v23, v70, v71
	v_cvt_pk_bf16_f32 v24, v72, v73
	v_cvt_pk_bf16_f32 v25, v74, v75
	ds_read_b32 v84, v9 offset:96
	ds_read_b32 v85, v9 offset:228
	ds_read_b32 v86, v9 offset:360
	ds_read_b32 v87, v9 offset:492
	ds_read_b32 v88, v9 offset:624
	ds_read_b32 v89, v9 offset:756
	ds_read_b32 v90, v9 offset:888
	ds_read_b32 v91, v9 offset:1020
	v_or_b32_e32 v21, s8, v10
	v_mul_u32_u24_e32 v21, 0xb00, v21
	v_lshlrev_b32_e32 v26, 1, v21
	v_mov_b32_e32 v27, v165
	v_lshl_add_u64 v[26:27], v[6:7], 0, v[26:27]
	global_store_dwordx4 v[26:27], v[22:25], off
	s_nop 1
	s_waitcnt lgkmcnt(8)
	v_cvt_pk_bf16_f32 v22, v76, v77
	v_cvt_pk_bf16_f32 v23, v78, v79
	v_cvt_pk_bf16_f32 v24, v80, v81
	v_cvt_pk_bf16_f32 v25, v82, v83
	v_or_b32_e32 v21, s8, v11
	v_mul_u32_u24_e32 v21, 0xb00, v21
	v_lshlrev_b32_e32 v26, 1, v21
	v_mov_b32_e32 v27, v165
	v_lshl_add_u64 v[26:27], v[6:7], 0, v[26:27]
	global_store_dwordx4 v[26:27], v[22:25], off
	s_nop 1
	s_waitcnt lgkmcnt(0)
	v_cvt_pk_bf16_f32 v22, v84, v85
	v_cvt_pk_bf16_f32 v23, v86, v87
	v_cvt_pk_bf16_f32 v24, v88, v89
	v_cvt_pk_bf16_f32 v25, v90, v91
	v_or_b32_e32 v21, s8, v12
	v_mul_u32_u24_e32 v21, 0xb00, v21
	v_lshlrev_b32_e32 v26, 1, v21
	v_mov_b32_e32 v27, v165
	v_lshl_add_u64 v[6:7], v[6:7], 0, v[26:27]
	global_store_dwordx4 v[6:7], v[22:25], off
	s_nop 1
	s_waitcnt lgkmcnt(0)
	v_writelane_b32 v240, s9, 63
	s_mov_b64 s[8:9], 0
